# P3 and P4 epilogues both hand-written with loads three row blocks ahead and interleaved row-sum reductions
# speedup vs baseline: 1.0084x; 1.0016x over previous
; __device__ __forceinline__ unsigned cvt_pk_bf16(float lo, float hi) { unsigned r; asm volatile("v_cvt_pk_bf16_f32 %0, %1, %2" : "=v"(r) : "v"(lo), "v"(hi)); return r; }
;     __device__ __forceinline__ void operator()(const f32x4 (&acc)[2][2][4][2], const Unit& u, int wr, int wc, int fr, int fq) const {
;     ...
;             for (int m = 0; m < 4; ++m) { const int row = row0 + ai * HALF + m * 16;
;                 const float* xr = (row < MP ? xp + (size_t)row * DM : xs + (size_t)(row - MP) * DM) + col0;
;                 bf16_t* brow = h2b + (size_t)row * DM + col0; float ss = 0.f;
; #pragma unroll
;                 for (int bj = 0; bj < 2; ++bj) { const f32x4 x0 = *(const f32x4*)(xr + bj * HALF), x1 = *(const f32x4*)(xr + bj * HALF + 4);
;                     const f32x4 v0 = acc[ai][bj][m][0] + x0, v1 = acc[ai][bj][m][1] + x1;
;                     u32x4 w; w.x = cvt_pk_bf16(v0[0], v0[1]); w.y = cvt_pk_bf16(v0[2], v0[3]); w.z = cvt_pk_bf16(v1[0], v1[1]); w.w = cvt_pk_bf16(v1[2], v1[3]);
;                     *(u32x4*)(brow + bj * HALF) = w;
;                     ss += v0[0] * v0[0] + v0[1] * v0[1] + v0[2] * v0[2] + v0[3] * v0[3] + v1[0] * v1[0] + v1[1] * v1[1] + v1[2] * v1[2] + v1[3] * v1[3]; }
;                 ss += __shfl_xor(ss, 16); ss += __shfl_xor(ss, 32);
;                 if (fq == 0) atomicAdd(rowss + row, ss); }
.LBB0_516:
	v_lshl_add_u32 v156, s28, 8, v135
	v_readlane_b32 s52, v249, 14
	v_readlane_b32 s53, v249, 15
	v_readlane_b32 s54, v249, 16
	v_readlane_b32 s55, v249, 17
	v_readlane_b32 s56, v249, 18
	v_readlane_b32 s57, v249, 19
	v_readlane_b32 s58, v249, 20
	v_readlane_b32 s59, v249, 21
	v_readlane_b32 s60, v249, 22
	v_readlane_b32 s61, v249, 23
	v_readlane_b32 s62, v249, 24
	v_readlane_b32 s63, v249, 25
	v_readlane_b32 s64, v249, 26
	v_readlane_b32 s65, v249, 27
	v_readlane_b32 s66, v249, 28
	v_readlane_b32 s67, v249, 29
	v_lshl_or_b32 v158, s26, 8, v167
	v_lshlrev_b32_e32 v160, 12, v156
	v_lshl_add_u32 v160, v158, 2, v160
	v_lshlrev_b32_e32 v161, 11, v156
	v_lshl_add_u32 v161, v158, 1, v161
	v_lshlrev_b32_e32 v146, 2, v156
	v_xor_b32_e32 v159, 16, v209
	v_lshlrev_b32_e32 v159, 2, v159
	v_xor_b32_e32 v234, 32, v209
	v_lshlrev_b32_e32 v234, 2, v234
	global_load_dwordx4 v[172:175], v160, s[52:53]
	global_load_dwordx4 v[176:179], v160, s[52:53] offset:16
	global_load_dwordx4 v[180:183], v160, s[52:53] offset:512
	global_load_dwordx4 v[184:187], v160, s[52:53] offset:528
	v_add_u32_e32 v157, 0x10000, v160
	global_load_dwordx4 v[188:191], v157, s[52:53]
	global_load_dwordx4 v[192:195], v157, s[52:53] offset:16
	global_load_dwordx4 v[196:199], v157, s[52:53] offset:512
	global_load_dwordx4 v[200:203], v157, s[52:53] offset:528
	v_add_u32_e32 v157, 0x20000, v160
	global_load_dwordx4 v[210:213], v157, s[52:53]
	global_load_dwordx4 v[214:217], v157, s[52:53] offset:16
	global_load_dwordx4 v[218:221], v157, s[52:53] offset:512
	global_load_dwordx4 v[222:225], v157, s[52:53] offset:528
	s_waitcnt vmcnt(8)
	v_pk_add_f32 v[124:125], v[124:125], v[172:173]
	v_pk_add_f32 v[126:127], v[126:127], v[174:175]
	v_pk_add_f32 v[120:121], v[120:121], v[176:177]
	v_pk_add_f32 v[122:123], v[122:123], v[178:179]
	v_pk_add_f32 v[116:117], v[116:117], v[180:181]
	v_pk_add_f32 v[118:119], v[118:119], v[182:183]
	v_pk_add_f32 v[112:113], v[112:113], v[184:185]
	v_pk_add_f32 v[114:115], v[114:115], v[186:187]
	v_mul_f32_e32 v226, v125, v125
	v_fmac_f32_e32 v226, v124, v124
	v_fmac_f32_e32 v226, v126, v126
	v_fmac_f32_e32 v226, v127, v127
	v_fmac_f32_e32 v226, v120, v120
	v_fmac_f32_e32 v226, v121, v121
	v_fmac_f32_e32 v226, v122, v122
	v_fmac_f32_e32 v226, v123, v123
	v_mul_f32_e32 v157, v117, v117
	v_fmac_f32_e32 v157, v116, v116
	v_fmac_f32_e32 v157, v118, v118
	v_fmac_f32_e32 v157, v119, v119
	v_fmac_f32_e32 v157, v112, v112
	v_fmac_f32_e32 v157, v113, v113
	v_fmac_f32_e32 v157, v114, v114
	v_fmac_f32_e32 v157, v115, v115
	v_add_f32_e32 v226, v226, v157
	ds_bpermute_b32 v235, v159, v226
	v_cvt_pk_bf16_f32 v172, v124, v125
	v_cvt_pk_bf16_f32 v173, v126, v127
	v_cvt_pk_bf16_f32 v174, v120, v121
	v_cvt_pk_bf16_f32 v175, v122, v123
	v_cvt_pk_bf16_f32 v176, v116, v117
	v_cvt_pk_bf16_f32 v177, v118, v119
	v_cvt_pk_bf16_f32 v178, v112, v113
	v_cvt_pk_bf16_f32 v179, v114, v115
	global_store_dwordx4 v161, v[172:175], s[94:95]
	global_store_dwordx4 v161, v[176:179], s[94:95] offset:256
	s_nop 1
	v_add_u32_e32 v157, 0x30000, v160
	global_load_dwordx4 v[172:175], v157, s[52:53]
	global_load_dwordx4 v[176:179], v157, s[52:53] offset:16
	global_load_dwordx4 v[180:183], v157, s[52:53] offset:512
	global_load_dwordx4 v[184:187], v157, s[52:53] offset:528
	s_waitcnt vmcnt(10)
	v_pk_add_f32 v[108:109], v[108:109], v[188:189]
	v_pk_add_f32 v[110:111], v[110:111], v[190:191]
	v_pk_add_f32 v[104:105], v[104:105], v[192:193]
	v_pk_add_f32 v[106:107], v[106:107], v[194:195]
	v_pk_add_f32 v[100:101], v[100:101], v[196:197]
	v_pk_add_f32 v[102:103], v[102:103], v[198:199]
	v_pk_add_f32 v[96:97], v[96:97], v[200:201]
	v_pk_add_f32 v[98:99], v[98:99], v[202:203]
	v_mul_f32_e32 v227, v109, v109
	v_fmac_f32_e32 v227, v108, v108
	v_fmac_f32_e32 v227, v110, v110
	v_fmac_f32_e32 v227, v111, v111
	v_fmac_f32_e32 v227, v104, v104
	v_fmac_f32_e32 v227, v105, v105
	v_fmac_f32_e32 v227, v106, v106
	v_fmac_f32_e32 v227, v107, v107
	v_mul_f32_e32 v157, v101, v101
	v_fmac_f32_e32 v157, v100, v100
	v_fmac_f32_e32 v157, v102, v102
	v_fmac_f32_e32 v157, v103, v103
	v_fmac_f32_e32 v157, v96, v96
	v_fmac_f32_e32 v157, v97, v97
	v_fmac_f32_e32 v157, v98, v98
	v_fmac_f32_e32 v157, v99, v99
	v_add_f32_e32 v227, v227, v157
	s_waitcnt lgkmcnt(0)
	v_add_f32_e32 v226, v226, v235
	ds_bpermute_b32 v235, v234, v226
	ds_bpermute_b32 v236, v159, v227
	v_cvt_pk_bf16_f32 v188, v108, v109
	v_cvt_pk_bf16_f32 v189, v110, v111
	v_cvt_pk_bf16_f32 v190, v104, v105
	v_cvt_pk_bf16_f32 v191, v106, v107
	v_cvt_pk_bf16_f32 v192, v100, v101
	v_cvt_pk_bf16_f32 v193, v102, v103
	v_cvt_pk_bf16_f32 v194, v96, v97
	v_cvt_pk_bf16_f32 v195, v98, v99
	v_add_u32_e32 v157, 0x8000, v161
	global_store_dwordx4 v157, v[188:191], s[94:95]
	global_store_dwordx4 v157, v[192:195], s[94:95] offset:256
	s_waitcnt lgkmcnt(0)
	v_add_f32_e32 v226, v226, v235
	s_mov_b64 exec, s[4:5]
	global_atomic_add_f32 v146, v226, s[10:11]
	s_mov_b64 exec, -1
	s_nop 1
	v_add_u32_e32 v157, 0x80000, v160
	global_load_dwordx4 v[188:191], v157, s[52:53]
	global_load_dwordx4 v[192:195], v157, s[52:53] offset:16
	global_load_dwordx4 v[196:199], v157, s[52:53] offset:512
	global_load_dwordx4 v[200:203], v157, s[52:53] offset:528
	s_waitcnt vmcnt(13)
; __device__ __forceinline__ unsigned cvt_pk_bf16(float lo, float hi) { unsigned r; asm volatile("v_cvt_pk_bf16_f32 %0, %1, %2" : "=v"(r) : "v"(lo), "v"(hi)); return r; }
;     __device__ __forceinline__ void operator()(const f32x4 (&acc)[2][2][4][2], const Unit& u, int wr, int wc, int fr, int fq) const {
;     ...
;             for (int m = 0; m < 4; ++m) { const int row = row0 + ai * HALF + m * 16;
;                 const float* xr = (row < MP ? xp + (size_t)row * DM : xs + (size_t)(row - MP) * DM) + col0;
;                 bf16_t* brow = h2b + (size_t)row * DM + col0; float ss = 0.f;
; #pragma unroll
;                 for (int bj = 0; bj < 2; ++bj) { const f32x4 x0 = *(const f32x4*)(xr + bj * HALF), x1 = *(const f32x4*)(xr + bj * HALF + 4);
;                     const f32x4 v0 = acc[ai][bj][m][0] + x0, v1 = acc[ai][bj][m][1] + x1;
;                     u32x4 w; w.x = cvt_pk_bf16(v0[0], v0[1]); w.y = cvt_pk_bf16(v0[2], v0[3]); w.z = cvt_pk_bf16(v1[0], v1[1]); w.w = cvt_pk_bf16(v1[2], v1[3]);
;                     *(u32x4*)(brow + bj * HALF) = w;
;                     ss += v0[0] * v0[0] + v0[1] * v0[1] + v0[2] * v0[2] + v0[3] * v0[3] + v1[0] * v1[0] + v1[1] * v1[1] + v1[2] * v1[2] + v1[3] * v1[3]; }
;                 ss += __shfl_xor(ss, 16); ss += __shfl_xor(ss, 32);
;                 if (fq == 0) atomicAdd(rowss + row, ss); }
	v_pk_add_f32 v[92:93], v[92:93], v[210:211]
	v_pk_add_f32 v[94:95], v[94:95], v[212:213]
	v_pk_add_f32 v[88:89], v[88:89], v[214:215]
	v_pk_add_f32 v[90:91], v[90:91], v[216:217]
	v_pk_add_f32 v[84:85], v[84:85], v[218:219]
	v_pk_add_f32 v[86:87], v[86:87], v[220:221]
	v_pk_add_f32 v[80:81], v[80:81], v[222:223]
	v_pk_add_f32 v[82:83], v[82:83], v[224:225]
	v_mul_f32_e32 v228, v93, v93
	v_fmac_f32_e32 v228, v92, v92
	v_fmac_f32_e32 v228, v94, v94
	v_fmac_f32_e32 v228, v95, v95
	v_fmac_f32_e32 v228, v88, v88
	v_fmac_f32_e32 v228, v89, v89
	v_fmac_f32_e32 v228, v90, v90
	v_fmac_f32_e32 v228, v91, v91
	v_mul_f32_e32 v157, v85, v85
	v_fmac_f32_e32 v157, v84, v84
	v_fmac_f32_e32 v157, v86, v86
	v_fmac_f32_e32 v157, v87, v87
	v_fmac_f32_e32 v157, v80, v80
	v_fmac_f32_e32 v157, v81, v81
	v_fmac_f32_e32 v157, v82, v82
	v_fmac_f32_e32 v157, v83, v83
	v_add_f32_e32 v228, v228, v157
	s_waitcnt lgkmcnt(0)
	v_add_f32_e32 v227, v227, v236
	ds_bpermute_b32 v236, v234, v227
	ds_bpermute_b32 v235, v159, v228
	v_cvt_pk_bf16_f32 v210, v92, v93
	v_cvt_pk_bf16_f32 v211, v94, v95
	v_cvt_pk_bf16_f32 v212, v88, v89
	v_cvt_pk_bf16_f32 v213, v90, v91
	v_cvt_pk_bf16_f32 v214, v84, v85
	v_cvt_pk_bf16_f32 v215, v86, v87
	v_cvt_pk_bf16_f32 v216, v80, v81
	v_cvt_pk_bf16_f32 v217, v82, v83
	v_add_u32_e32 v157, 0x10000, v161
	global_store_dwordx4 v157, v[210:213], s[94:95]
	global_store_dwordx4 v157, v[214:217], s[94:95] offset:256
	s_waitcnt lgkmcnt(0)
	v_add_f32_e32 v227, v227, v236
	s_mov_b64 exec, s[4:5]
	global_atomic_add_f32 v146, v227, s[10:11] offset:64
	s_mov_b64 exec, -1
	s_nop 1
	v_add_u32_e32 v157, 0x90000, v160
	global_load_dwordx4 v[210:213], v157, s[52:53]
	global_load_dwordx4 v[214:217], v157, s[52:53] offset:16
	global_load_dwordx4 v[218:221], v157, s[52:53] offset:512
	global_load_dwordx4 v[222:225], v157, s[52:53] offset:528
	s_waitcnt vmcnt(14)
	v_pk_add_f32 v[76:77], v[76:77], v[172:173]
	v_pk_add_f32 v[78:79], v[78:79], v[174:175]
	v_pk_add_f32 v[72:73], v[72:73], v[176:177]
	v_pk_add_f32 v[74:75], v[74:75], v[178:179]
	v_pk_add_f32 v[68:69], v[68:69], v[180:181]
	v_pk_add_f32 v[70:71], v[70:71], v[182:183]
	v_pk_add_f32 v[64:65], v[64:65], v[184:185]
	v_pk_add_f32 v[66:67], v[66:67], v[186:187]
	v_mul_f32_e32 v229, v77, v77
	v_fmac_f32_e32 v229, v76, v76
	v_fmac_f32_e32 v229, v78, v78
	v_fmac_f32_e32 v229, v79, v79
	v_fmac_f32_e32 v229, v72, v72
	v_fmac_f32_e32 v229, v73, v73
	v_fmac_f32_e32 v229, v74, v74
	v_fmac_f32_e32 v229, v75, v75
	v_mul_f32_e32 v157, v69, v69
	v_fmac_f32_e32 v157, v68, v68
	v_fmac_f32_e32 v157, v70, v70
	v_fmac_f32_e32 v157, v71, v71
	v_fmac_f32_e32 v157, v64, v64
	v_fmac_f32_e32 v157, v65, v65
	v_fmac_f32_e32 v157, v66, v66
	v_fmac_f32_e32 v157, v67, v67
	v_add_f32_e32 v229, v229, v157
	s_waitcnt lgkmcnt(0)
	v_add_f32_e32 v228, v228, v235
	ds_bpermute_b32 v235, v234, v228
	ds_bpermute_b32 v236, v159, v229
	v_cvt_pk_bf16_f32 v172, v76, v77
	v_cvt_pk_bf16_f32 v173, v78, v79
	v_cvt_pk_bf16_f32 v174, v72, v73
	v_cvt_pk_bf16_f32 v175, v74, v75
	v_cvt_pk_bf16_f32 v176, v68, v69
	v_cvt_pk_bf16_f32 v177, v70, v71
	v_cvt_pk_bf16_f32 v178, v64, v65
	v_cvt_pk_bf16_f32 v179, v66, v67
	v_add_u32_e32 v157, 0x18000, v161
	global_store_dwordx4 v157, v[172:175], s[94:95]
	global_store_dwordx4 v157, v[176:179], s[94:95] offset:256
	s_waitcnt lgkmcnt(0)
	v_add_f32_e32 v228, v228, v235
	s_mov_b64 exec, s[4:5]
	global_atomic_add_f32 v146, v228, s[10:11] offset:128
	s_mov_b64 exec, -1
	s_nop 1
	v_add_u32_e32 v157, 0xa0000, v160
	global_load_dwordx4 v[172:175], v157, s[52:53]
	global_load_dwordx4 v[176:179], v157, s[52:53] offset:16
	global_load_dwordx4 v[180:183], v157, s[52:53] offset:512
	global_load_dwordx4 v[184:187], v157, s[52:53] offset:528
	s_waitcnt vmcnt(14)
	v_pk_add_f32 v[60:61], v[60:61], v[188:189]
	v_pk_add_f32 v[62:63], v[62:63], v[190:191]
	v_pk_add_f32 v[56:57], v[56:57], v[192:193]
	v_pk_add_f32 v[58:59], v[58:59], v[194:195]
	v_pk_add_f32 v[52:53], v[52:53], v[196:197]
	v_pk_add_f32 v[54:55], v[54:55], v[198:199]
	v_pk_add_f32 v[48:49], v[48:49], v[200:201]
	v_pk_add_f32 v[50:51], v[50:51], v[202:203]
	v_mul_f32_e32 v230, v61, v61
	v_fmac_f32_e32 v230, v60, v60
	v_fmac_f32_e32 v230, v62, v62
	v_fmac_f32_e32 v230, v63, v63
	v_fmac_f32_e32 v230, v56, v56
	v_fmac_f32_e32 v230, v57, v57
	v_fmac_f32_e32 v230, v58, v58
	v_fmac_f32_e32 v230, v59, v59
	v_mul_f32_e32 v157, v53, v53
	v_fmac_f32_e32 v157, v52, v52
	v_fmac_f32_e32 v157, v54, v54
	v_fmac_f32_e32 v157, v55, v55
	v_fmac_f32_e32 v157, v48, v48
	v_fmac_f32_e32 v157, v49, v49
	v_fmac_f32_e32 v157, v50, v50
	v_fmac_f32_e32 v157, v51, v51
	v_add_f32_e32 v230, v230, v157
	s_waitcnt lgkmcnt(0)
	v_add_f32_e32 v229, v229, v236
	ds_bpermute_b32 v236, v234, v229
	ds_bpermute_b32 v235, v159, v230
	v_cvt_pk_bf16_f32 v188, v60, v61
	v_cvt_pk_bf16_f32 v189, v62, v63
	v_cvt_pk_bf16_f32 v190, v56, v57
	v_cvt_pk_bf16_f32 v191, v58, v59
	v_cvt_pk_bf16_f32 v192, v52, v53
	v_cvt_pk_bf16_f32 v193, v54, v55
	v_cvt_pk_bf16_f32 v194, v48, v49
	v_cvt_pk_bf16_f32 v195, v50, v51
	v_add_u32_e32 v157, 0x40000, v161
	global_store_dwordx4 v157, v[188:191], s[94:95]
	global_store_dwordx4 v157, v[192:195], s[94:95] offset:256
	s_waitcnt lgkmcnt(0)
; __device__ __forceinline__ unsigned cvt_pk_bf16(float lo, float hi) { unsigned r; asm volatile("v_cvt_pk_bf16_f32 %0, %1, %2" : "=v"(r) : "v"(lo), "v"(hi)); return r; }
;     __device__ __forceinline__ void operator()(const f32x4 (&acc)[2][2][4][2], const Unit& u, int wr, int wc, int fr, int fq) const {
;     ...
;             for (int m = 0; m < 4; ++m) { const int row = row0 + ai * HALF + m * 16;
;                 const float* xr = (row < MP ? xp + (size_t)row * DM : xs + (size_t)(row - MP) * DM) + col0;
;                 bf16_t* brow = h2b + (size_t)row * DM + col0; float ss = 0.f;
; #pragma unroll
;                 for (int bj = 0; bj < 2; ++bj) { const f32x4 x0 = *(const f32x4*)(xr + bj * HALF), x1 = *(const f32x4*)(xr + bj * HALF + 4);
;                     const f32x4 v0 = acc[ai][bj][m][0] + x0, v1 = acc[ai][bj][m][1] + x1;
;                     u32x4 w; w.x = cvt_pk_bf16(v0[0], v0[1]); w.y = cvt_pk_bf16(v0[2], v0[3]); w.z = cvt_pk_bf16(v1[0], v1[1]); w.w = cvt_pk_bf16(v1[2], v1[3]);
;                     *(u32x4*)(brow + bj * HALF) = w;
;                     ss += v0[0] * v0[0] + v0[1] * v0[1] + v0[2] * v0[2] + v0[3] * v0[3] + v1[0] * v1[0] + v1[1] * v1[1] + v1[2] * v1[2] + v1[3] * v1[3]; }
;                 ss += __shfl_xor(ss, 16); ss += __shfl_xor(ss, 32);
;                 if (fq == 0) atomicAdd(rowss + row, ss); }
	v_add_f32_e32 v229, v229, v236
	s_mov_b64 exec, s[4:5]
	global_atomic_add_f32 v146, v229, s[10:11] offset:192
	s_mov_b64 exec, -1
	s_nop 1
	v_add_u32_e32 v157, 0xb0000, v160
	global_load_dwordx4 v[188:191], v157, s[52:53]
	global_load_dwordx4 v[192:195], v157, s[52:53] offset:16
	global_load_dwordx4 v[196:199], v157, s[52:53] offset:512
	global_load_dwordx4 v[200:203], v157, s[52:53] offset:528
	s_waitcnt vmcnt(14)
	v_pk_add_f32 v[44:45], v[44:45], v[210:211]
	v_pk_add_f32 v[46:47], v[46:47], v[212:213]
	v_pk_add_f32 v[40:41], v[40:41], v[214:215]
	v_pk_add_f32 v[42:43], v[42:43], v[216:217]
	v_pk_add_f32 v[36:37], v[36:37], v[218:219]
	v_pk_add_f32 v[38:39], v[38:39], v[220:221]
	v_pk_add_f32 v[32:33], v[32:33], v[222:223]
	v_pk_add_f32 v[34:35], v[34:35], v[224:225]
	v_mul_f32_e32 v231, v45, v45
	v_fmac_f32_e32 v231, v44, v44
	v_fmac_f32_e32 v231, v46, v46
	v_fmac_f32_e32 v231, v47, v47
	v_fmac_f32_e32 v231, v40, v40
	v_fmac_f32_e32 v231, v41, v41
	v_fmac_f32_e32 v231, v42, v42
	v_fmac_f32_e32 v231, v43, v43
	v_mul_f32_e32 v157, v37, v37
	v_fmac_f32_e32 v157, v36, v36
	v_fmac_f32_e32 v157, v38, v38
	v_fmac_f32_e32 v157, v39, v39
	v_fmac_f32_e32 v157, v32, v32
	v_fmac_f32_e32 v157, v33, v33
	v_fmac_f32_e32 v157, v34, v34
	v_fmac_f32_e32 v157, v35, v35
	v_add_f32_e32 v231, v231, v157
	s_waitcnt lgkmcnt(0)
	v_add_f32_e32 v230, v230, v235
	ds_bpermute_b32 v235, v234, v230
	ds_bpermute_b32 v236, v159, v231
	v_cvt_pk_bf16_f32 v210, v44, v45
	v_cvt_pk_bf16_f32 v211, v46, v47
	v_cvt_pk_bf16_f32 v212, v40, v41
	v_cvt_pk_bf16_f32 v213, v42, v43
	v_cvt_pk_bf16_f32 v214, v36, v37
	v_cvt_pk_bf16_f32 v215, v38, v39
	v_cvt_pk_bf16_f32 v216, v32, v33
	v_cvt_pk_bf16_f32 v217, v34, v35
	v_add_u32_e32 v157, 0x48000, v161
	global_store_dwordx4 v157, v[210:213], s[94:95]
	global_store_dwordx4 v157, v[214:217], s[94:95] offset:256
	s_waitcnt lgkmcnt(0)
	v_add_f32_e32 v230, v230, v235
	s_mov_b64 exec, s[4:5]
	global_atomic_add_f32 v146, v230, s[10:11] offset:512
	s_mov_b64 exec, -1
	s_waitcnt vmcnt(10)
	v_pk_add_f32 v[28:29], v[28:29], v[172:173]
	v_pk_add_f32 v[30:31], v[30:31], v[174:175]
	v_pk_add_f32 v[24:25], v[24:25], v[176:177]
	v_pk_add_f32 v[26:27], v[26:27], v[178:179]
	v_pk_add_f32 v[20:21], v[20:21], v[180:181]
	v_pk_add_f32 v[22:23], v[22:23], v[182:183]
	v_pk_add_f32 v[16:17], v[16:17], v[184:185]
	v_pk_add_f32 v[18:19], v[18:19], v[186:187]
	v_mul_f32_e32 v232, v29, v29
	v_fmac_f32_e32 v232, v28, v28
	v_fmac_f32_e32 v232, v30, v30
	v_fmac_f32_e32 v232, v31, v31
	v_fmac_f32_e32 v232, v24, v24
	v_fmac_f32_e32 v232, v25, v25
	v_fmac_f32_e32 v232, v26, v26
	v_fmac_f32_e32 v232, v27, v27
	v_mul_f32_e32 v157, v21, v21
	v_fmac_f32_e32 v157, v20, v20
	v_fmac_f32_e32 v157, v22, v22
	v_fmac_f32_e32 v157, v23, v23
	v_fmac_f32_e32 v157, v16, v16
	v_fmac_f32_e32 v157, v17, v17
	v_fmac_f32_e32 v157, v18, v18
	v_fmac_f32_e32 v157, v19, v19
	v_add_f32_e32 v232, v232, v157
	s_waitcnt lgkmcnt(0)
	v_add_f32_e32 v231, v231, v236
	ds_bpermute_b32 v236, v234, v231
	ds_bpermute_b32 v235, v159, v232
	v_cvt_pk_bf16_f32 v172, v28, v29
	v_cvt_pk_bf16_f32 v173, v30, v31
	v_cvt_pk_bf16_f32 v174, v24, v25
	v_cvt_pk_bf16_f32 v175, v26, v27
	v_cvt_pk_bf16_f32 v176, v20, v21
	v_cvt_pk_bf16_f32 v177, v22, v23
	v_cvt_pk_bf16_f32 v178, v16, v17
	v_cvt_pk_bf16_f32 v179, v18, v19
	v_add_u32_e32 v157, 0x50000, v161
	global_store_dwordx4 v157, v[172:175], s[94:95]
	global_store_dwordx4 v157, v[176:179], s[94:95] offset:256
	s_waitcnt lgkmcnt(0)
	v_add_f32_e32 v231, v231, v236
	s_mov_b64 exec, s[4:5]
	global_atomic_add_f32 v146, v231, s[10:11] offset:576
	s_mov_b64 exec, -1
	s_waitcnt vmcnt(6)
	v_pk_add_f32 v[12:13], v[12:13], v[188:189]
	v_pk_add_f32 v[14:15], v[14:15], v[190:191]
	v_pk_add_f32 v[8:9], v[8:9], v[192:193]
	v_pk_add_f32 v[10:11], v[10:11], v[194:195]
	v_pk_add_f32 v[4:5], v[4:5], v[196:197]
	v_pk_add_f32 v[6:7], v[6:7], v[198:199]
	v_pk_add_f32 v[0:1], v[0:1], v[200:201]
	v_pk_add_f32 v[2:3], v[2:3], v[202:203]
	v_mul_f32_e32 v233, v13, v13
	v_fmac_f32_e32 v233, v12, v12
	v_fmac_f32_e32 v233, v14, v14
	v_fmac_f32_e32 v233, v15, v15
	v_fmac_f32_e32 v233, v8, v8
	v_fmac_f32_e32 v233, v9, v9
	v_fmac_f32_e32 v233, v10, v10
	v_fmac_f32_e32 v233, v11, v11
	v_mul_f32_e32 v157, v5, v5
	v_fmac_f32_e32 v157, v4, v4
	v_fmac_f32_e32 v157, v6, v6
	v_fmac_f32_e32 v157, v7, v7
	v_fmac_f32_e32 v157, v0, v0
	v_fmac_f32_e32 v157, v1, v1
	v_fmac_f32_e32 v157, v2, v2
	v_fmac_f32_e32 v157, v3, v3
	v_add_f32_e32 v233, v233, v157
	s_waitcnt lgkmcnt(0)
	v_add_f32_e32 v232, v232, v235
	ds_bpermute_b32 v235, v234, v232
	ds_bpermute_b32 v236, v159, v233
	v_cvt_pk_bf16_f32 v188, v12, v13
	v_cvt_pk_bf16_f32 v189, v14, v15
	v_cvt_pk_bf16_f32 v190, v8, v9
	v_cvt_pk_bf16_f32 v191, v10, v11
	v_cvt_pk_bf16_f32 v192, v4, v5
	v_cvt_pk_bf16_f32 v193, v6, v7
	v_cvt_pk_bf16_f32 v194, v0, v1
	v_cvt_pk_bf16_f32 v195, v2, v3
	v_add_u32_e32 v157, 0x58000, v161
	global_store_dwordx4 v157, v[188:191], s[94:95]
	global_store_dwordx4 v157, v[192:195], s[94:95] offset:256
	s_waitcnt lgkmcnt(0)
	v_add_f32_e32 v232, v232, v235
	s_mov_b64 exec, s[4:5]
	global_atomic_add_f32 v146, v232, s[10:11] offset:640
	s_mov_b64 exec, -1
	s_waitcnt lgkmcnt(0)
	v_add_f32_e32 v233, v233, v236
	ds_bpermute_b32 v236, v234, v233
	s_waitcnt lgkmcnt(0)
	v_add_f32_e32 v233, v233, v236
	s_mov_b64 exec, s[4:5]
	global_atomic_add_f32 v146, v233, s[10:11] offset:704
	s_mov_b64 exec, -1

; __device__ __forceinline__ void unpack8(u32x4 u, float* f) { f[0] = bflo(u.x); f[1] = bfhi(u.x); f[2] = bflo(u.y); f[3] = bfhi(u.y); f[4] = bflo(u.z); f[5] = bfhi(u.z); f[6] = bflo(u.w); f[7] = bfhi(u.w); }
; __device__ __forceinline__ float sigmoidf_(float x) { return __builtin_amdgcn_rcpf(1.f + __expf(-x)); }
; __device__ __forceinline__ unsigned cvt_pk_bf16(float lo, float hi) { unsigned r; asm volatile("v_cvt_pk_bf16_f32 %0, %1, %2" : "=v"(r) : "v"(lo), "v"(hi)); return r; }
;     __device__ __forceinline__ void operator()(const f32x4 (&acc)[2][2][4][2], const Unit& u, int wr, int wc, int fr, int fq) const {
;         const int row0 = u.pm * BM + wr * 64 + fr; const int col0 = u.pn * BM + wc * 32 + 8 * fq;
; #pragma unroll
;         for (int ai = 0; ai < 2; ++ai)
; #pragma unroll
;             for (int m = 0; m < 4; ++m) { const int row = row0 + ai * HALF + m * 16;
;                 const float rstd = __builtin_amdgcn_rsqf(rowss2[row] * (1.f / DM) + NORM_EPS);
;                 const bf16_t* hrow = h2b + (size_t)row * DM + col0; bf16_t* orow = h3b + (size_t)row * DM + col0; const bf16_t* prow = pp + (size_t)row * DM + col0; float ss = 0.f;
; #pragma unroll
;                 for (int bj = 0; bj < 2; ++bj) { const u32x4 hw = *(const u32x4*)(hrow + bj * HALF); float hf[8]; unpack8(hw, hf);
;                     const u32x4 pw = *(const u32x4*)(prow + bj * HALF); float pf[8]; unpack8(pw, pf);
;                     const f32x4 a0 = acc[ai][bj][m][0], a1 = acc[ai][bj][m][1]; f32x4 v0, v1;
; #pragma unroll
;                     for (int e = 0; e < 4; ++e) { v0[e] = hf[e] + sigmoidf_(a0[e] * rstd) * pf[e]; v1[e] = hf[4 + e] + sigmoidf_(a1[e] * rstd) * pf[4 + e]; }
;                     u32x4 w; w.x = cvt_pk_bf16(v0[0], v0[1]); w.y = cvt_pk_bf16(v0[2], v0[3]); w.z = cvt_pk_bf16(v1[0], v1[1]); w.w = cvt_pk_bf16(v1[2], v1[3]);
;                     *(u32x4*)(orow + bj * HALF) = w;
;                     ss += v0[0] * v0[0] + v0[1] * v0[1] + v0[2] * v0[2] + v0[3] * v0[3] + v1[0] * v1[0] + v1[1] * v1[1] + v1[2] * v1[2] + v1[3] * v1[3]; }
;                 ss += __shfl_xor(ss, 16); ss += __shfl_xor(ss, 32);
;                 if (fq == 0) atomicAdd(rowss3 + row, ss); }
.LBB0_610:
	v_lshl_add_u32 v154, s28, 8, v135
	v_lshl_or_b32 v158, s30, 8, v161
	v_lshlrev_b32_e32 v156, 11, v154
	v_lshl_add_u32 v156, v158, 1, v156
	v_lshlrev_b32_e32 v157, 2, v154
	v_xor_b32_e32 v154, 16, v209
	v_lshlrev_b32_e32 v154, 2, v154
	v_xor_b32_e32 v221, 32, v209
	v_lshlrev_b32_e32 v221, 2, v221
	global_load_dword v214, v157, s[10:11]
	global_load_dwordx4 v[164:167], v156, s[94:95]
	global_load_dwordx4 v[168:171], v156, s[76:77]
	global_load_dwordx4 v[172:175], v156, s[94:95] offset:256
	global_load_dwordx4 v[176:179], v156, s[76:77] offset:256
	global_load_dword v215, v157, s[10:11] offset:64
	v_add_u32_e32 v158, 0x8000, v156
	global_load_dwordx4 v[180:183], v158, s[94:95]
	global_load_dwordx4 v[184:187], v158, s[76:77]
	global_load_dwordx4 v[188:191], v158, s[94:95] offset:256
	global_load_dwordx4 v[192:195], v158, s[76:77] offset:256
	global_load_dword v216, v157, s[10:11] offset:128
	v_add_u32_e32 v158, 0x10000, v156
	global_load_dwordx4 v[196:199], v158, s[94:95]
	global_load_dwordx4 v[200:203], v158, s[76:77]
	global_load_dwordx4 v[204:207], v158, s[94:95] offset:256
	global_load_dwordx4 v[210:213], v158, s[76:77] offset:256
	s_waitcnt vmcnt(10)
	v_fmamk_f32 v214, v214, 0x3a800000, v163
	v_rsq_f32_e32 v214, v214
	v_lshlrev_b32_e32 v152, 16, v164
	v_and_b32_e32 v153, 0xffff0000, v164
	v_lshlrev_b32_e32 v155, 16, v165
	v_and_b32_e32 v159, 0xffff0000, v165
	v_lshlrev_b32_e32 v217, 16, v166
	v_and_b32_e32 v218, 0xffff0000, v166
	v_lshlrev_b32_e32 v219, 16, v167
	v_and_b32_e32 v220, 0xffff0000, v167
	v_lshlrev_b32_e32 v164, 16, v168
	v_and_b32_e32 v168, 0xffff0000, v168
	v_lshlrev_b32_e32 v165, 16, v169
	v_and_b32_e32 v169, 0xffff0000, v169
	v_lshlrev_b32_e32 v166, 16, v170
	v_and_b32_e32 v170, 0xffff0000, v170
	v_lshlrev_b32_e32 v167, 16, v171
	v_and_b32_e32 v171, 0xffff0000, v171
	v_mul_f32_e32 v124, v124, v214
	v_mul_f32_e32 v125, v125, v214
	v_mul_f32_e32 v126, v126, v214
	v_mul_f32_e32 v127, v127, v214
	v_mul_f32_e32 v120, v120, v214
	v_mul_f32_e32 v121, v121, v214
	v_mul_f32_e32 v122, v122, v214
	v_mul_f32_e32 v123, v123, v214
	v_mul_f32_e32 v124, 0xbfb8aa3b, v124
	v_mul_f32_e32 v125, 0xbfb8aa3b, v125
	v_mul_f32_e32 v126, 0xbfb8aa3b, v126
	v_mul_f32_e32 v127, 0xbfb8aa3b, v127
	v_mul_f32_e32 v120, 0xbfb8aa3b, v120
	v_mul_f32_e32 v121, 0xbfb8aa3b, v121
	v_mul_f32_e32 v122, 0xbfb8aa3b, v122
	v_mul_f32_e32 v123, 0xbfb8aa3b, v123
	v_exp_f32_e32 v124, v124
	v_exp_f32_e32 v125, v125
	v_exp_f32_e32 v126, v126
	v_exp_f32_e32 v127, v127
	v_exp_f32_e32 v120, v120
	v_exp_f32_e32 v121, v121
	v_exp_f32_e32 v122, v122
	v_exp_f32_e32 v123, v123
	v_add_f32_e32 v124, 1.0, v124
	v_add_f32_e32 v125, 1.0, v125
	v_add_f32_e32 v126, 1.0, v126
	v_add_f32_e32 v127, 1.0, v127
	v_add_f32_e32 v120, 1.0, v120
	v_add_f32_e32 v121, 1.0, v121
	v_add_f32_e32 v122, 1.0, v122
	v_add_f32_e32 v123, 1.0, v123
	v_rcp_f32_e32 v124, v124
	v_rcp_f32_e32 v125, v125
	v_rcp_f32_e32 v126, v126
	v_rcp_f32_e32 v127, v127
	v_rcp_f32_e32 v120, v120
	v_rcp_f32_e32 v121, v121
	v_rcp_f32_e32 v122, v122
	v_rcp_f32_e32 v123, v123
	v_fmac_f32_e32 v152, v124, v164
	v_fmac_f32_e32 v153, v125, v168
	v_fmac_f32_e32 v155, v126, v165
	v_fmac_f32_e32 v159, v127, v169
	v_fmac_f32_e32 v217, v120, v166
	v_fmac_f32_e32 v218, v121, v170
	v_fmac_f32_e32 v219, v122, v167
	v_fmac_f32_e32 v220, v123, v171
	v_mul_f32_e32 v127, v153, v153
	v_fmac_f32_e32 v127, v152, v152
	v_fmac_f32_e32 v127, v155, v155
	v_fmac_f32_e32 v127, v159, v159
	v_fmac_f32_e32 v127, v217, v217
	v_fmac_f32_e32 v127, v218, v218
	v_fmac_f32_e32 v127, v219, v219
	v_fmac_f32_e32 v127, v220, v220
	v_cvt_pk_bf16_f32 v164, v152, v153
	v_cvt_pk_bf16_f32 v165, v155, v159
	v_cvt_pk_bf16_f32 v166, v217, v218
	v_cvt_pk_bf16_f32 v167, v219, v220
	global_store_dwordx4 v156, v[164:167], s[68:69]
	v_lshlrev_b32_e32 v152, 16, v172
	v_and_b32_e32 v153, 0xffff0000, v172
	v_lshlrev_b32_e32 v155, 16, v173
	v_and_b32_e32 v159, 0xffff0000, v173
	v_lshlrev_b32_e32 v217, 16, v174
	v_and_b32_e32 v218, 0xffff0000, v174
	v_lshlrev_b32_e32 v219, 16, v175
	v_and_b32_e32 v220, 0xffff0000, v175
	v_lshlrev_b32_e32 v172, 16, v176
	v_and_b32_e32 v176, 0xffff0000, v176
	v_lshlrev_b32_e32 v173, 16, v177
	v_and_b32_e32 v177, 0xffff0000, v177
	v_lshlrev_b32_e32 v174, 16, v178
	v_and_b32_e32 v178, 0xffff0000, v178
	v_lshlrev_b32_e32 v175, 16, v179
	v_and_b32_e32 v179, 0xffff0000, v179
	v_mul_f32_e32 v116, v116, v214
	v_mul_f32_e32 v117, v117, v214
	v_mul_f32_e32 v118, v118, v214
	v_mul_f32_e32 v119, v119, v214
	v_mul_f32_e32 v112, v112, v214
	v_mul_f32_e32 v113, v113, v214
	v_mul_f32_e32 v114, v114, v214
	v_mul_f32_e32 v115, v115, v214
	v_mul_f32_e32 v116, 0xbfb8aa3b, v116
	v_mul_f32_e32 v117, 0xbfb8aa3b, v117
	v_mul_f32_e32 v118, 0xbfb8aa3b, v118
	v_mul_f32_e32 v119, 0xbfb8aa3b, v119
	v_mul_f32_e32 v112, 0xbfb8aa3b, v112
	v_mul_f32_e32 v113, 0xbfb8aa3b, v113
	v_mul_f32_e32 v114, 0xbfb8aa3b, v114
	v_mul_f32_e32 v115, 0xbfb8aa3b, v115
	v_exp_f32_e32 v116, v116
	v_exp_f32_e32 v117, v117
	v_exp_f32_e32 v118, v118
	v_exp_f32_e32 v119, v119
	v_exp_f32_e32 v112, v112
	v_exp_f32_e32 v113, v113
	v_exp_f32_e32 v114, v114
	v_exp_f32_e32 v115, v115
	v_add_f32_e32 v116, 1.0, v116
	v_add_f32_e32 v117, 1.0, v117
	v_add_f32_e32 v118, 1.0, v118
	v_add_f32_e32 v119, 1.0, v119
	v_add_f32_e32 v112, 1.0, v112
	v_add_f32_e32 v113, 1.0, v113
	v_add_f32_e32 v114, 1.0, v114
	v_add_f32_e32 v115, 1.0, v115
	v_rcp_f32_e32 v116, v116
	v_rcp_f32_e32 v117, v117
	v_rcp_f32_e32 v118, v118
	v_rcp_f32_e32 v119, v119
	v_rcp_f32_e32 v112, v112
	v_rcp_f32_e32 v113, v113
	v_rcp_f32_e32 v114, v114
	v_rcp_f32_e32 v115, v115
	v_fmac_f32_e32 v152, v116, v172
	v_fmac_f32_e32 v153, v117, v176
	v_fmac_f32_e32 v155, v118, v173
	v_fmac_f32_e32 v159, v119, v177
	v_fmac_f32_e32 v217, v112, v174
	v_fmac_f32_e32 v218, v113, v178
	v_fmac_f32_e32 v219, v114, v175
	v_fmac_f32_e32 v220, v115, v179
	v_mul_f32_e32 v158, v153, v153
	v_fmac_f32_e32 v158, v152, v152
	v_fmac_f32_e32 v158, v155, v155
	v_fmac_f32_e32 v158, v159, v159
	v_fmac_f32_e32 v158, v217, v217
	v_fmac_f32_e32 v158, v218, v218
	v_fmac_f32_e32 v158, v219, v219
	v_fmac_f32_e32 v158, v220, v220
	v_add_f32_e32 v127, v127, v158
	ds_bpermute_b32 v126, v154, v127
	v_cvt_pk_bf16_f32 v172, v152, v153
	v_cvt_pk_bf16_f32 v173, v155, v159
	v_cvt_pk_bf16_f32 v174, v217, v218
	v_cvt_pk_bf16_f32 v175, v219, v220
	global_store_dwordx4 v156, v[172:175], s[68:69] offset:256
	s_nop 1
	global_load_dword v214, v157, s[10:11] offset:192
	v_add_u32_e32 v158, 0x18000, v156
	global_load_dwordx4 v[164:167], v158, s[94:95]
	global_load_dwordx4 v[168:171], v158, s[76:77]
	global_load_dwordx4 v[172:175], v158, s[94:95] offset:256
	global_load_dwordx4 v[176:179], v158, s[76:77] offset:256
	s_waitcnt vmcnt(12)
; __device__ __forceinline__ void unpack8(u32x4 u, float* f) { f[0] = bflo(u.x); f[1] = bfhi(u.x); f[2] = bflo(u.y); f[3] = bfhi(u.y); f[4] = bflo(u.z); f[5] = bfhi(u.z); f[6] = bflo(u.w); f[7] = bfhi(u.w); }
; __device__ __forceinline__ float sigmoidf_(float x) { return __builtin_amdgcn_rcpf(1.f + __expf(-x)); }
; __device__ __forceinline__ unsigned cvt_pk_bf16(float lo, float hi) { unsigned r; asm volatile("v_cvt_pk_bf16_f32 %0, %1, %2" : "=v"(r) : "v"(lo), "v"(hi)); return r; }
;     __device__ __forceinline__ void operator()(const f32x4 (&acc)[2][2][4][2], const Unit& u, int wr, int wc, int fr, int fq) const {
;         const int row0 = u.pm * BM + wr * 64 + fr; const int col0 = u.pn * BM + wc * 32 + 8 * fq;
; #pragma unroll
;         for (int ai = 0; ai < 2; ++ai)
; #pragma unroll
;             for (int m = 0; m < 4; ++m) { const int row = row0 + ai * HALF + m * 16;
;                 const float rstd = __builtin_amdgcn_rsqf(rowss2[row] * (1.f / DM) + NORM_EPS);
;                 const bf16_t* hrow = h2b + (size_t)row * DM + col0; bf16_t* orow = h3b + (size_t)row * DM + col0; const bf16_t* prow = pp + (size_t)row * DM + col0; float ss = 0.f;
; #pragma unroll
;                 for (int bj = 0; bj < 2; ++bj) { const u32x4 hw = *(const u32x4*)(hrow + bj * HALF); float hf[8]; unpack8(hw, hf);
;                     const u32x4 pw = *(const u32x4*)(prow + bj * HALF); float pf[8]; unpack8(pw, pf);
;                     const f32x4 a0 = acc[ai][bj][m][0], a1 = acc[ai][bj][m][1]; f32x4 v0, v1;
; #pragma unroll
;                     for (int e = 0; e < 4; ++e) { v0[e] = hf[e] + sigmoidf_(a0[e] * rstd) * pf[e]; v1[e] = hf[4 + e] + sigmoidf_(a1[e] * rstd) * pf[4 + e]; }
;                     u32x4 w; w.x = cvt_pk_bf16(v0[0], v0[1]); w.y = cvt_pk_bf16(v0[2], v0[3]); w.z = cvt_pk_bf16(v1[0], v1[1]); w.w = cvt_pk_bf16(v1[2], v1[3]);
;                     *(u32x4*)(orow + bj * HALF) = w;
;                     ss += v0[0] * v0[0] + v0[1] * v0[1] + v0[2] * v0[2] + v0[3] * v0[3] + v1[0] * v1[0] + v1[1] * v1[1] + v1[2] * v1[2] + v1[3] * v1[3]; }
;                 ss += __shfl_xor(ss, 16); ss += __shfl_xor(ss, 32);
;                 if (fq == 0) atomicAdd(rowss3 + row, ss); }
	v_fmamk_f32 v215, v215, 0x3a800000, v163
	v_rsq_f32_e32 v215, v215
	v_lshlrev_b32_e32 v152, 16, v180
	v_and_b32_e32 v153, 0xffff0000, v180
	v_lshlrev_b32_e32 v155, 16, v181
	v_and_b32_e32 v159, 0xffff0000, v181
	v_lshlrev_b32_e32 v217, 16, v182
	v_and_b32_e32 v218, 0xffff0000, v182
	v_lshlrev_b32_e32 v219, 16, v183
	v_and_b32_e32 v220, 0xffff0000, v183
	v_lshlrev_b32_e32 v180, 16, v184
	v_and_b32_e32 v184, 0xffff0000, v184
	v_lshlrev_b32_e32 v181, 16, v185
	v_and_b32_e32 v185, 0xffff0000, v185
	v_lshlrev_b32_e32 v182, 16, v186
	v_and_b32_e32 v186, 0xffff0000, v186
	v_lshlrev_b32_e32 v183, 16, v187
	v_and_b32_e32 v187, 0xffff0000, v187
	v_mul_f32_e32 v108, v108, v215
	v_mul_f32_e32 v109, v109, v215
	v_mul_f32_e32 v110, v110, v215
	v_mul_f32_e32 v111, v111, v215
	v_mul_f32_e32 v104, v104, v215
	v_mul_f32_e32 v105, v105, v215
	v_mul_f32_e32 v106, v106, v215
	v_mul_f32_e32 v107, v107, v215
	v_mul_f32_e32 v108, 0xbfb8aa3b, v108
	v_mul_f32_e32 v109, 0xbfb8aa3b, v109
	v_mul_f32_e32 v110, 0xbfb8aa3b, v110
	v_mul_f32_e32 v111, 0xbfb8aa3b, v111
	v_mul_f32_e32 v104, 0xbfb8aa3b, v104
	v_mul_f32_e32 v105, 0xbfb8aa3b, v105
	v_mul_f32_e32 v106, 0xbfb8aa3b, v106
	v_mul_f32_e32 v107, 0xbfb8aa3b, v107
	v_exp_f32_e32 v108, v108
	v_exp_f32_e32 v109, v109
	v_exp_f32_e32 v110, v110
	v_exp_f32_e32 v111, v111
	v_exp_f32_e32 v104, v104
	v_exp_f32_e32 v105, v105
	v_exp_f32_e32 v106, v106
	v_exp_f32_e32 v107, v107
	v_add_f32_e32 v108, 1.0, v108
	v_add_f32_e32 v109, 1.0, v109
	v_add_f32_e32 v110, 1.0, v110
	v_add_f32_e32 v111, 1.0, v111
	v_add_f32_e32 v104, 1.0, v104
	v_add_f32_e32 v105, 1.0, v105
	v_add_f32_e32 v106, 1.0, v106
	v_add_f32_e32 v107, 1.0, v107
	v_rcp_f32_e32 v108, v108
	v_rcp_f32_e32 v109, v109
	v_rcp_f32_e32 v110, v110
	v_rcp_f32_e32 v111, v111
	v_rcp_f32_e32 v104, v104
	v_rcp_f32_e32 v105, v105
	v_rcp_f32_e32 v106, v106
	v_rcp_f32_e32 v107, v107
	v_fmac_f32_e32 v152, v108, v180
	v_fmac_f32_e32 v153, v109, v184
	v_fmac_f32_e32 v155, v110, v181
	v_fmac_f32_e32 v159, v111, v185
	v_fmac_f32_e32 v217, v104, v182
	v_fmac_f32_e32 v218, v105, v186
	v_fmac_f32_e32 v219, v106, v183
	v_fmac_f32_e32 v220, v107, v187
	v_mul_f32_e32 v111, v153, v153
	v_fmac_f32_e32 v111, v152, v152
	v_fmac_f32_e32 v111, v155, v155
	v_fmac_f32_e32 v111, v159, v159
	v_fmac_f32_e32 v111, v217, v217
	v_fmac_f32_e32 v111, v218, v218
	v_fmac_f32_e32 v111, v219, v219
	v_fmac_f32_e32 v111, v220, v220
	v_cvt_pk_bf16_f32 v180, v152, v153
	v_cvt_pk_bf16_f32 v181, v155, v159
	v_cvt_pk_bf16_f32 v182, v217, v218
	v_cvt_pk_bf16_f32 v183, v219, v220
	v_add_u32_e32 v184, 0x8000, v156
	global_store_dwordx4 v184, v[180:183], s[68:69]
	v_lshlrev_b32_e32 v152, 16, v188
	v_and_b32_e32 v153, 0xffff0000, v188
	v_lshlrev_b32_e32 v155, 16, v189
	v_and_b32_e32 v159, 0xffff0000, v189
	v_lshlrev_b32_e32 v217, 16, v190
	v_and_b32_e32 v218, 0xffff0000, v190
	v_lshlrev_b32_e32 v219, 16, v191
	v_and_b32_e32 v220, 0xffff0000, v191
	v_lshlrev_b32_e32 v188, 16, v192
	v_and_b32_e32 v192, 0xffff0000, v192
	v_lshlrev_b32_e32 v189, 16, v193
	v_and_b32_e32 v193, 0xffff0000, v193
	v_lshlrev_b32_e32 v190, 16, v194
	v_and_b32_e32 v194, 0xffff0000, v194
	v_lshlrev_b32_e32 v191, 16, v195
	v_and_b32_e32 v195, 0xffff0000, v195
	v_mul_f32_e32 v100, v100, v215
	v_mul_f32_e32 v101, v101, v215
	v_mul_f32_e32 v102, v102, v215
	v_mul_f32_e32 v103, v103, v215
	v_mul_f32_e32 v96, v96, v215
	v_mul_f32_e32 v97, v97, v215
	v_mul_f32_e32 v98, v98, v215
	v_mul_f32_e32 v99, v99, v215
	v_mul_f32_e32 v100, 0xbfb8aa3b, v100
	v_mul_f32_e32 v101, 0xbfb8aa3b, v101
	v_mul_f32_e32 v102, 0xbfb8aa3b, v102
	v_mul_f32_e32 v103, 0xbfb8aa3b, v103
	v_mul_f32_e32 v96, 0xbfb8aa3b, v96
	v_mul_f32_e32 v97, 0xbfb8aa3b, v97
	v_mul_f32_e32 v98, 0xbfb8aa3b, v98
	v_mul_f32_e32 v99, 0xbfb8aa3b, v99
	v_exp_f32_e32 v100, v100
	v_exp_f32_e32 v101, v101
	v_exp_f32_e32 v102, v102
	v_exp_f32_e32 v103, v103
	v_exp_f32_e32 v96, v96
	v_exp_f32_e32 v97, v97
	v_exp_f32_e32 v98, v98
	v_exp_f32_e32 v99, v99
	v_add_f32_e32 v100, 1.0, v100
	v_add_f32_e32 v101, 1.0, v101
	v_add_f32_e32 v102, 1.0, v102
	v_add_f32_e32 v103, 1.0, v103
	v_add_f32_e32 v96, 1.0, v96
	v_add_f32_e32 v97, 1.0, v97
	v_add_f32_e32 v98, 1.0, v98
	v_add_f32_e32 v99, 1.0, v99
	v_rcp_f32_e32 v100, v100
	v_rcp_f32_e32 v101, v101
	v_rcp_f32_e32 v102, v102
	v_rcp_f32_e32 v103, v103
	v_rcp_f32_e32 v96, v96
	v_rcp_f32_e32 v97, v97
	v_rcp_f32_e32 v98, v98
	v_rcp_f32_e32 v99, v99
	v_fmac_f32_e32 v152, v100, v188
	v_fmac_f32_e32 v153, v101, v192
	v_fmac_f32_e32 v155, v102, v189
	v_fmac_f32_e32 v159, v103, v193
	v_fmac_f32_e32 v217, v96, v190
	v_fmac_f32_e32 v218, v97, v194
	v_fmac_f32_e32 v219, v98, v191
	v_fmac_f32_e32 v220, v99, v195
	v_mul_f32_e32 v158, v153, v153
	v_fmac_f32_e32 v158, v152, v152
	v_fmac_f32_e32 v158, v155, v155
	v_fmac_f32_e32 v158, v159, v159
	v_fmac_f32_e32 v158, v217, v217
	v_fmac_f32_e32 v158, v218, v218
	v_fmac_f32_e32 v158, v219, v219
	v_fmac_f32_e32 v158, v220, v220
	v_add_f32_e32 v111, v111, v158
	s_waitcnt lgkmcnt(0)
	v_add_f32_e32 v127, v127, v126
	ds_bpermute_b32 v126, v221, v127
	ds_bpermute_b32 v110, v154, v111
	v_cvt_pk_bf16_f32 v188, v152, v153
	v_cvt_pk_bf16_f32 v189, v155, v159
	v_cvt_pk_bf16_f32 v190, v217, v218
	v_cvt_pk_bf16_f32 v191, v219, v220
	v_add_u32_e32 v192, 0x8000, v156
	global_store_dwordx4 v192, v[188:191], s[68:69] offset:256
	s_waitcnt lgkmcnt(0)
	v_add_f32_e32 v127, v127, v126
	s_mov_b64 exec, s[6:7]
	global_atomic_add_f32 v157, v127, s[12:13]
	s_mov_b64 exec, -1
	s_nop 1
	global_load_dword v215, v157, s[10:11] offset:512
	v_add_u32_e32 v158, 0x40000, v156
	global_load_dwordx4 v[180:183], v158, s[94:95]
	global_load_dwordx4 v[184:187], v158, s[76:77]
	global_load_dwordx4 v[188:191], v158, s[94:95] offset:256
	global_load_dwordx4 v[192:195], v158, s[76:77] offset:256
	s_waitcnt vmcnt(15)
; __device__ __forceinline__ void unpack8(u32x4 u, float* f) { f[0] = bflo(u.x); f[1] = bfhi(u.x); f[2] = bflo(u.y); f[3] = bfhi(u.y); f[4] = bflo(u.z); f[5] = bfhi(u.z); f[6] = bflo(u.w); f[7] = bfhi(u.w); }
; __device__ __forceinline__ float sigmoidf_(float x) { return __builtin_amdgcn_rcpf(1.f + __expf(-x)); }
; __device__ __forceinline__ unsigned cvt_pk_bf16(float lo, float hi) { unsigned r; asm volatile("v_cvt_pk_bf16_f32 %0, %1, %2" : "=v"(r) : "v"(lo), "v"(hi)); return r; }
;     __device__ __forceinline__ void operator()(const f32x4 (&acc)[2][2][4][2], const Unit& u, int wr, int wc, int fr, int fq) const {
;         const int row0 = u.pm * BM + wr * 64 + fr; const int col0 = u.pn * BM + wc * 32 + 8 * fq;
; #pragma unroll
;         for (int ai = 0; ai < 2; ++ai)
; #pragma unroll
;             for (int m = 0; m < 4; ++m) { const int row = row0 + ai * HALF + m * 16;
;                 const float rstd = __builtin_amdgcn_rsqf(rowss2[row] * (1.f / DM) + NORM_EPS);
;                 const bf16_t* hrow = h2b + (size_t)row * DM + col0; bf16_t* orow = h3b + (size_t)row * DM + col0; const bf16_t* prow = pp + (size_t)row * DM + col0; float ss = 0.f;
; #pragma unroll
;                 for (int bj = 0; bj < 2; ++bj) { const u32x4 hw = *(const u32x4*)(hrow + bj * HALF); float hf[8]; unpack8(hw, hf);
;                     const u32x4 pw = *(const u32x4*)(prow + bj * HALF); float pf[8]; unpack8(pw, pf);
;                     const f32x4 a0 = acc[ai][bj][m][0], a1 = acc[ai][bj][m][1]; f32x4 v0, v1;
; #pragma unroll
;                     for (int e = 0; e < 4; ++e) { v0[e] = hf[e] + sigmoidf_(a0[e] * rstd) * pf[e]; v1[e] = hf[4 + e] + sigmoidf_(a1[e] * rstd) * pf[4 + e]; }
;                     u32x4 w; w.x = cvt_pk_bf16(v0[0], v0[1]); w.y = cvt_pk_bf16(v0[2], v0[3]); w.z = cvt_pk_bf16(v1[0], v1[1]); w.w = cvt_pk_bf16(v1[2], v1[3]);
;                     *(u32x4*)(orow + bj * HALF) = w;
;                     ss += v0[0] * v0[0] + v0[1] * v0[1] + v0[2] * v0[2] + v0[3] * v0[3] + v1[0] * v1[0] + v1[1] * v1[1] + v1[2] * v1[2] + v1[3] * v1[3]; }
;                 ss += __shfl_xor(ss, 16); ss += __shfl_xor(ss, 32);
;                 if (fq == 0) atomicAdd(rowss3 + row, ss); }
	v_fmamk_f32 v216, v216, 0x3a800000, v163
	v_rsq_f32_e32 v216, v216
	v_lshlrev_b32_e32 v152, 16, v196
	v_and_b32_e32 v153, 0xffff0000, v196
	v_lshlrev_b32_e32 v155, 16, v197
	v_and_b32_e32 v159, 0xffff0000, v197
	v_lshlrev_b32_e32 v217, 16, v198
	v_and_b32_e32 v218, 0xffff0000, v198
	v_lshlrev_b32_e32 v219, 16, v199
	v_and_b32_e32 v220, 0xffff0000, v199
	v_lshlrev_b32_e32 v196, 16, v200
	v_and_b32_e32 v200, 0xffff0000, v200
	v_lshlrev_b32_e32 v197, 16, v201
	v_and_b32_e32 v201, 0xffff0000, v201
	v_lshlrev_b32_e32 v198, 16, v202
	v_and_b32_e32 v202, 0xffff0000, v202
	v_lshlrev_b32_e32 v199, 16, v203
	v_and_b32_e32 v203, 0xffff0000, v203
	v_mul_f32_e32 v92, v92, v216
	v_mul_f32_e32 v93, v93, v216
	v_mul_f32_e32 v94, v94, v216
	v_mul_f32_e32 v95, v95, v216
	v_mul_f32_e32 v88, v88, v216
	v_mul_f32_e32 v89, v89, v216
	v_mul_f32_e32 v90, v90, v216
	v_mul_f32_e32 v91, v91, v216
	v_mul_f32_e32 v92, 0xbfb8aa3b, v92
	v_mul_f32_e32 v93, 0xbfb8aa3b, v93
	v_mul_f32_e32 v94, 0xbfb8aa3b, v94
	v_mul_f32_e32 v95, 0xbfb8aa3b, v95
	v_mul_f32_e32 v88, 0xbfb8aa3b, v88
	v_mul_f32_e32 v89, 0xbfb8aa3b, v89
	v_mul_f32_e32 v90, 0xbfb8aa3b, v90
	v_mul_f32_e32 v91, 0xbfb8aa3b, v91
	v_exp_f32_e32 v92, v92
	v_exp_f32_e32 v93, v93
	v_exp_f32_e32 v94, v94
	v_exp_f32_e32 v95, v95
	v_exp_f32_e32 v88, v88
	v_exp_f32_e32 v89, v89
	v_exp_f32_e32 v90, v90
	v_exp_f32_e32 v91, v91
	v_add_f32_e32 v92, 1.0, v92
	v_add_f32_e32 v93, 1.0, v93
	v_add_f32_e32 v94, 1.0, v94
	v_add_f32_e32 v95, 1.0, v95
	v_add_f32_e32 v88, 1.0, v88
	v_add_f32_e32 v89, 1.0, v89
	v_add_f32_e32 v90, 1.0, v90
	v_add_f32_e32 v91, 1.0, v91
	v_rcp_f32_e32 v92, v92
	v_rcp_f32_e32 v93, v93
	v_rcp_f32_e32 v94, v94
	v_rcp_f32_e32 v95, v95
	v_rcp_f32_e32 v88, v88
	v_rcp_f32_e32 v89, v89
	v_rcp_f32_e32 v90, v90
	v_rcp_f32_e32 v91, v91
	v_fmac_f32_e32 v152, v92, v196
	v_fmac_f32_e32 v153, v93, v200
	v_fmac_f32_e32 v155, v94, v197
	v_fmac_f32_e32 v159, v95, v201
	v_fmac_f32_e32 v217, v88, v198
	v_fmac_f32_e32 v218, v89, v202
	v_fmac_f32_e32 v219, v90, v199
	v_fmac_f32_e32 v220, v91, v203
	v_mul_f32_e32 v95, v153, v153
	v_fmac_f32_e32 v95, v152, v152
	v_fmac_f32_e32 v95, v155, v155
	v_fmac_f32_e32 v95, v159, v159
	v_fmac_f32_e32 v95, v217, v217
	v_fmac_f32_e32 v95, v218, v218
	v_fmac_f32_e32 v95, v219, v219
	v_fmac_f32_e32 v95, v220, v220
	v_cvt_pk_bf16_f32 v196, v152, v153
	v_cvt_pk_bf16_f32 v197, v155, v159
	v_cvt_pk_bf16_f32 v198, v217, v218
	v_cvt_pk_bf16_f32 v199, v219, v220
	v_add_u32_e32 v200, 0x10000, v156
	global_store_dwordx4 v200, v[196:199], s[68:69]
	v_lshlrev_b32_e32 v152, 16, v204
	v_and_b32_e32 v153, 0xffff0000, v204
	v_lshlrev_b32_e32 v155, 16, v205
	v_and_b32_e32 v159, 0xffff0000, v205
	v_lshlrev_b32_e32 v217, 16, v206
	v_and_b32_e32 v218, 0xffff0000, v206
	v_lshlrev_b32_e32 v219, 16, v207
	v_and_b32_e32 v220, 0xffff0000, v207
	v_lshlrev_b32_e32 v204, 16, v210
	v_and_b32_e32 v210, 0xffff0000, v210
	v_lshlrev_b32_e32 v205, 16, v211
	v_and_b32_e32 v211, 0xffff0000, v211
	v_lshlrev_b32_e32 v206, 16, v212
	v_and_b32_e32 v212, 0xffff0000, v212
	v_lshlrev_b32_e32 v207, 16, v213
	v_and_b32_e32 v213, 0xffff0000, v213
	v_mul_f32_e32 v84, v84, v216
	v_mul_f32_e32 v85, v85, v216
	v_mul_f32_e32 v86, v86, v216
	v_mul_f32_e32 v87, v87, v216
	v_mul_f32_e32 v80, v80, v216
	v_mul_f32_e32 v81, v81, v216
	v_mul_f32_e32 v82, v82, v216
	v_mul_f32_e32 v83, v83, v216
	v_mul_f32_e32 v84, 0xbfb8aa3b, v84
	v_mul_f32_e32 v85, 0xbfb8aa3b, v85
	v_mul_f32_e32 v86, 0xbfb8aa3b, v86
	v_mul_f32_e32 v87, 0xbfb8aa3b, v87
	v_mul_f32_e32 v80, 0xbfb8aa3b, v80
	v_mul_f32_e32 v81, 0xbfb8aa3b, v81
	v_mul_f32_e32 v82, 0xbfb8aa3b, v82
	v_mul_f32_e32 v83, 0xbfb8aa3b, v83
	v_exp_f32_e32 v84, v84
	v_exp_f32_e32 v85, v85
	v_exp_f32_e32 v86, v86
	v_exp_f32_e32 v87, v87
	v_exp_f32_e32 v80, v80
	v_exp_f32_e32 v81, v81
	v_exp_f32_e32 v82, v82
	v_exp_f32_e32 v83, v83
	v_add_f32_e32 v84, 1.0, v84
	v_add_f32_e32 v85, 1.0, v85
	v_add_f32_e32 v86, 1.0, v86
	v_add_f32_e32 v87, 1.0, v87
	v_add_f32_e32 v80, 1.0, v80
	v_add_f32_e32 v81, 1.0, v81
	v_add_f32_e32 v82, 1.0, v82
	v_add_f32_e32 v83, 1.0, v83
	v_rcp_f32_e32 v84, v84
	v_rcp_f32_e32 v85, v85
	v_rcp_f32_e32 v86, v86
	v_rcp_f32_e32 v87, v87
	v_rcp_f32_e32 v80, v80
	v_rcp_f32_e32 v81, v81
	v_rcp_f32_e32 v82, v82
	v_rcp_f32_e32 v83, v83
	v_fmac_f32_e32 v152, v84, v204
	v_fmac_f32_e32 v153, v85, v210
	v_fmac_f32_e32 v155, v86, v205
	v_fmac_f32_e32 v159, v87, v211
	v_fmac_f32_e32 v217, v80, v206
	v_fmac_f32_e32 v218, v81, v212
	v_fmac_f32_e32 v219, v82, v207
	v_fmac_f32_e32 v220, v83, v213
	v_mul_f32_e32 v158, v153, v153
	v_fmac_f32_e32 v158, v152, v152
	v_fmac_f32_e32 v158, v155, v155
	v_fmac_f32_e32 v158, v159, v159
	v_fmac_f32_e32 v158, v217, v217
	v_fmac_f32_e32 v158, v218, v218
	v_fmac_f32_e32 v158, v219, v219
	v_fmac_f32_e32 v158, v220, v220
	v_add_f32_e32 v95, v95, v158
	s_waitcnt lgkmcnt(0)
	v_add_f32_e32 v111, v111, v110
	ds_bpermute_b32 v110, v221, v111
	ds_bpermute_b32 v94, v154, v95
	v_cvt_pk_bf16_f32 v204, v152, v153
	v_cvt_pk_bf16_f32 v205, v155, v159
	v_cvt_pk_bf16_f32 v206, v217, v218
	v_cvt_pk_bf16_f32 v207, v219, v220
	v_add_u32_e32 v210, 0x10000, v156
	global_store_dwordx4 v210, v[204:207], s[68:69] offset:256
	s_waitcnt lgkmcnt(0)
	v_add_f32_e32 v111, v111, v110
	s_mov_b64 exec, s[6:7]
	global_atomic_add_f32 v157, v111, s[12:13] offset:64
	s_mov_b64 exec, -1
	s_nop 1
	global_load_dword v216, v157, s[10:11] offset:576
	v_add_u32_e32 v158, 0x48000, v156
	global_load_dwordx4 v[196:199], v158, s[94:95]
	global_load_dwordx4 v[200:203], v158, s[76:77]
	global_load_dwordx4 v[204:207], v158, s[94:95] offset:256
	global_load_dwordx4 v[210:213], v158, s[76:77] offset:256
	s_waitcnt vmcnt(16)
; __device__ __forceinline__ void unpack8(u32x4 u, float* f) { f[0] = bflo(u.x); f[1] = bfhi(u.x); f[2] = bflo(u.y); f[3] = bfhi(u.y); f[4] = bflo(u.z); f[5] = bfhi(u.z); f[6] = bflo(u.w); f[7] = bfhi(u.w); }
; __device__ __forceinline__ float sigmoidf_(float x) { return __builtin_amdgcn_rcpf(1.f + __expf(-x)); }
; __device__ __forceinline__ unsigned cvt_pk_bf16(float lo, float hi) { unsigned r; asm volatile("v_cvt_pk_bf16_f32 %0, %1, %2" : "=v"(r) : "v"(lo), "v"(hi)); return r; }
;     __device__ __forceinline__ void operator()(const f32x4 (&acc)[2][2][4][2], const Unit& u, int wr, int wc, int fr, int fq) const {
;         const int row0 = u.pm * BM + wr * 64 + fr; const int col0 = u.pn * BM + wc * 32 + 8 * fq;
; #pragma unroll
;         for (int ai = 0; ai < 2; ++ai)
; #pragma unroll
;             for (int m = 0; m < 4; ++m) { const int row = row0 + ai * HALF + m * 16;
;                 const float rstd = __builtin_amdgcn_rsqf(rowss2[row] * (1.f / DM) + NORM_EPS);
;                 const bf16_t* hrow = h2b + (size_t)row * DM + col0; bf16_t* orow = h3b + (size_t)row * DM + col0; const bf16_t* prow = pp + (size_t)row * DM + col0; float ss = 0.f;
; #pragma unroll
;                 for (int bj = 0; bj < 2; ++bj) { const u32x4 hw = *(const u32x4*)(hrow + bj * HALF); float hf[8]; unpack8(hw, hf);
;                     const u32x4 pw = *(const u32x4*)(prow + bj * HALF); float pf[8]; unpack8(pw, pf);
;                     const f32x4 a0 = acc[ai][bj][m][0], a1 = acc[ai][bj][m][1]; f32x4 v0, v1;
; #pragma unroll
;                     for (int e = 0; e < 4; ++e) { v0[e] = hf[e] + sigmoidf_(a0[e] * rstd) * pf[e]; v1[e] = hf[4 + e] + sigmoidf_(a1[e] * rstd) * pf[4 + e]; }
;                     u32x4 w; w.x = cvt_pk_bf16(v0[0], v0[1]); w.y = cvt_pk_bf16(v0[2], v0[3]); w.z = cvt_pk_bf16(v1[0], v1[1]); w.w = cvt_pk_bf16(v1[2], v1[3]);
;                     *(u32x4*)(orow + bj * HALF) = w;
;                     ss += v0[0] * v0[0] + v0[1] * v0[1] + v0[2] * v0[2] + v0[3] * v0[3] + v1[0] * v1[0] + v1[1] * v1[1] + v1[2] * v1[2] + v1[3] * v1[3]; }
;                 ss += __shfl_xor(ss, 16); ss += __shfl_xor(ss, 32);
;                 if (fq == 0) atomicAdd(rowss3 + row, ss); }
	v_fmamk_f32 v214, v214, 0x3a800000, v163
	v_rsq_f32_e32 v214, v214
	v_lshlrev_b32_e32 v152, 16, v164
	v_and_b32_e32 v153, 0xffff0000, v164
	v_lshlrev_b32_e32 v155, 16, v165
	v_and_b32_e32 v159, 0xffff0000, v165
	v_lshlrev_b32_e32 v217, 16, v166
	v_and_b32_e32 v218, 0xffff0000, v166
	v_lshlrev_b32_e32 v219, 16, v167
	v_and_b32_e32 v220, 0xffff0000, v167
	v_lshlrev_b32_e32 v164, 16, v168
	v_and_b32_e32 v168, 0xffff0000, v168
	v_lshlrev_b32_e32 v165, 16, v169
	v_and_b32_e32 v169, 0xffff0000, v169
	v_lshlrev_b32_e32 v166, 16, v170
	v_and_b32_e32 v170, 0xffff0000, v170
	v_lshlrev_b32_e32 v167, 16, v171
	v_and_b32_e32 v171, 0xffff0000, v171
	v_mul_f32_e32 v76, v76, v214
	v_mul_f32_e32 v77, v77, v214
	v_mul_f32_e32 v78, v78, v214
	v_mul_f32_e32 v79, v79, v214
	v_mul_f32_e32 v72, v72, v214
	v_mul_f32_e32 v73, v73, v214
	v_mul_f32_e32 v74, v74, v214
	v_mul_f32_e32 v75, v75, v214
	v_mul_f32_e32 v76, 0xbfb8aa3b, v76
	v_mul_f32_e32 v77, 0xbfb8aa3b, v77
	v_mul_f32_e32 v78, 0xbfb8aa3b, v78
	v_mul_f32_e32 v79, 0xbfb8aa3b, v79
	v_mul_f32_e32 v72, 0xbfb8aa3b, v72
	v_mul_f32_e32 v73, 0xbfb8aa3b, v73
	v_mul_f32_e32 v74, 0xbfb8aa3b, v74
	v_mul_f32_e32 v75, 0xbfb8aa3b, v75
	v_exp_f32_e32 v76, v76
	v_exp_f32_e32 v77, v77
	v_exp_f32_e32 v78, v78
	v_exp_f32_e32 v79, v79
	v_exp_f32_e32 v72, v72
	v_exp_f32_e32 v73, v73
	v_exp_f32_e32 v74, v74
	v_exp_f32_e32 v75, v75
	v_add_f32_e32 v76, 1.0, v76
	v_add_f32_e32 v77, 1.0, v77
	v_add_f32_e32 v78, 1.0, v78
	v_add_f32_e32 v79, 1.0, v79
	v_add_f32_e32 v72, 1.0, v72
	v_add_f32_e32 v73, 1.0, v73
	v_add_f32_e32 v74, 1.0, v74
	v_add_f32_e32 v75, 1.0, v75
	v_rcp_f32_e32 v76, v76
	v_rcp_f32_e32 v77, v77
	v_rcp_f32_e32 v78, v78
	v_rcp_f32_e32 v79, v79
	v_rcp_f32_e32 v72, v72
	v_rcp_f32_e32 v73, v73
	v_rcp_f32_e32 v74, v74
	v_rcp_f32_e32 v75, v75
	v_fmac_f32_e32 v152, v76, v164
	v_fmac_f32_e32 v153, v77, v168
	v_fmac_f32_e32 v155, v78, v165
	v_fmac_f32_e32 v159, v79, v169
	v_fmac_f32_e32 v217, v72, v166
	v_fmac_f32_e32 v218, v73, v170
	v_fmac_f32_e32 v219, v74, v167
	v_fmac_f32_e32 v220, v75, v171
	v_mul_f32_e32 v79, v153, v153
	v_fmac_f32_e32 v79, v152, v152
	v_fmac_f32_e32 v79, v155, v155
	v_fmac_f32_e32 v79, v159, v159
	v_fmac_f32_e32 v79, v217, v217
	v_fmac_f32_e32 v79, v218, v218
	v_fmac_f32_e32 v79, v219, v219
	v_fmac_f32_e32 v79, v220, v220
	v_cvt_pk_bf16_f32 v164, v152, v153
	v_cvt_pk_bf16_f32 v165, v155, v159
	v_cvt_pk_bf16_f32 v166, v217, v218
	v_cvt_pk_bf16_f32 v167, v219, v220
	v_add_u32_e32 v168, 0x18000, v156
	global_store_dwordx4 v168, v[164:167], s[68:69]
	v_lshlrev_b32_e32 v152, 16, v172
	v_and_b32_e32 v153, 0xffff0000, v172
	v_lshlrev_b32_e32 v155, 16, v173
	v_and_b32_e32 v159, 0xffff0000, v173
	v_lshlrev_b32_e32 v217, 16, v174
	v_and_b32_e32 v218, 0xffff0000, v174
	v_lshlrev_b32_e32 v219, 16, v175
	v_and_b32_e32 v220, 0xffff0000, v175
	v_lshlrev_b32_e32 v172, 16, v176
	v_and_b32_e32 v176, 0xffff0000, v176
	v_lshlrev_b32_e32 v173, 16, v177
	v_and_b32_e32 v177, 0xffff0000, v177
	v_lshlrev_b32_e32 v174, 16, v178
	v_and_b32_e32 v178, 0xffff0000, v178
	v_lshlrev_b32_e32 v175, 16, v179
	v_and_b32_e32 v179, 0xffff0000, v179
	v_mul_f32_e32 v68, v68, v214
	v_mul_f32_e32 v69, v69, v214
	v_mul_f32_e32 v70, v70, v214
	v_mul_f32_e32 v71, v71, v214
	v_mul_f32_e32 v64, v64, v214
	v_mul_f32_e32 v65, v65, v214
	v_mul_f32_e32 v66, v66, v214
	v_mul_f32_e32 v67, v67, v214
	v_mul_f32_e32 v68, 0xbfb8aa3b, v68
	v_mul_f32_e32 v69, 0xbfb8aa3b, v69
	v_mul_f32_e32 v70, 0xbfb8aa3b, v70
	v_mul_f32_e32 v71, 0xbfb8aa3b, v71
	v_mul_f32_e32 v64, 0xbfb8aa3b, v64
	v_mul_f32_e32 v65, 0xbfb8aa3b, v65
	v_mul_f32_e32 v66, 0xbfb8aa3b, v66
	v_mul_f32_e32 v67, 0xbfb8aa3b, v67
	v_exp_f32_e32 v68, v68
	v_exp_f32_e32 v69, v69
	v_exp_f32_e32 v70, v70
	v_exp_f32_e32 v71, v71
	v_exp_f32_e32 v64, v64
	v_exp_f32_e32 v65, v65
	v_exp_f32_e32 v66, v66
	v_exp_f32_e32 v67, v67
	v_add_f32_e32 v68, 1.0, v68
	v_add_f32_e32 v69, 1.0, v69
	v_add_f32_e32 v70, 1.0, v70
	v_add_f32_e32 v71, 1.0, v71
	v_add_f32_e32 v64, 1.0, v64
	v_add_f32_e32 v65, 1.0, v65
	v_add_f32_e32 v66, 1.0, v66
	v_add_f32_e32 v67, 1.0, v67
	v_rcp_f32_e32 v68, v68
	v_rcp_f32_e32 v69, v69
	v_rcp_f32_e32 v70, v70
	v_rcp_f32_e32 v71, v71
	v_rcp_f32_e32 v64, v64
	v_rcp_f32_e32 v65, v65
	v_rcp_f32_e32 v66, v66
	v_rcp_f32_e32 v67, v67
	v_fmac_f32_e32 v152, v68, v172
	v_fmac_f32_e32 v153, v69, v176
	v_fmac_f32_e32 v155, v70, v173
	v_fmac_f32_e32 v159, v71, v177
	v_fmac_f32_e32 v217, v64, v174
	v_fmac_f32_e32 v218, v65, v178
	v_fmac_f32_e32 v219, v66, v175
	v_fmac_f32_e32 v220, v67, v179
	v_mul_f32_e32 v158, v153, v153
	v_fmac_f32_e32 v158, v152, v152
	v_fmac_f32_e32 v158, v155, v155
	v_fmac_f32_e32 v158, v159, v159
	v_fmac_f32_e32 v158, v217, v217
	v_fmac_f32_e32 v158, v218, v218
	v_fmac_f32_e32 v158, v219, v219
	v_fmac_f32_e32 v158, v220, v220
	v_add_f32_e32 v79, v79, v158
	s_waitcnt lgkmcnt(0)
	v_add_f32_e32 v95, v95, v94
	ds_bpermute_b32 v94, v221, v95
	ds_bpermute_b32 v78, v154, v79
	v_cvt_pk_bf16_f32 v172, v152, v153
	v_cvt_pk_bf16_f32 v173, v155, v159
	v_cvt_pk_bf16_f32 v174, v217, v218
	v_cvt_pk_bf16_f32 v175, v219, v220
	v_add_u32_e32 v176, 0x18000, v156
	global_store_dwordx4 v176, v[172:175], s[68:69] offset:256
	s_waitcnt lgkmcnt(0)
	v_add_f32_e32 v95, v95, v94
	s_mov_b64 exec, s[6:7]
	global_atomic_add_f32 v157, v95, s[12:13] offset:128
	s_mov_b64 exec, -1
	s_nop 1
	global_load_dword v214, v157, s[10:11] offset:640
	v_add_u32_e32 v158, 0x50000, v156
	global_load_dwordx4 v[164:167], v158, s[94:95]
	global_load_dwordx4 v[168:171], v158, s[76:77]
	global_load_dwordx4 v[172:175], v158, s[94:95] offset:256
	global_load_dwordx4 v[176:179], v158, s[76:77] offset:256
	s_waitcnt vmcnt(16)
; __device__ __forceinline__ void unpack8(u32x4 u, float* f) { f[0] = bflo(u.x); f[1] = bfhi(u.x); f[2] = bflo(u.y); f[3] = bfhi(u.y); f[4] = bflo(u.z); f[5] = bfhi(u.z); f[6] = bflo(u.w); f[7] = bfhi(u.w); }
; __device__ __forceinline__ float sigmoidf_(float x) { return __builtin_amdgcn_rcpf(1.f + __expf(-x)); }
; __device__ __forceinline__ unsigned cvt_pk_bf16(float lo, float hi) { unsigned r; asm volatile("v_cvt_pk_bf16_f32 %0, %1, %2" : "=v"(r) : "v"(lo), "v"(hi)); return r; }
;     __device__ __forceinline__ void operator()(const f32x4 (&acc)[2][2][4][2], const Unit& u, int wr, int wc, int fr, int fq) const {
;     ...
;             for (int m = 0; m < 4; ++m) { const int row = row0 + ai * HALF + m * 16;
;                 const float rstd = __builtin_amdgcn_rsqf(rowss2[row] * (1.f / DM) + NORM_EPS);
;                 const bf16_t* hrow = h2b + (size_t)row * DM + col0; bf16_t* orow = h3b + (size_t)row * DM + col0; const bf16_t* prow = pp + (size_t)row * DM + col0; float ss = 0.f;
; #pragma unroll
;                 for (int bj = 0; bj < 2; ++bj) { const u32x4 hw = *(const u32x4*)(hrow + bj * HALF); float hf[8]; unpack8(hw, hf);
;                     const u32x4 pw = *(const u32x4*)(prow + bj * HALF); float pf[8]; unpack8(pw, pf);
;                     const f32x4 a0 = acc[ai][bj][m][0], a1 = acc[ai][bj][m][1]; f32x4 v0, v1;
; #pragma unroll
;                     for (int e = 0; e < 4; ++e) { v0[e] = hf[e] + sigmoidf_(a0[e] * rstd) * pf[e]; v1[e] = hf[4 + e] + sigmoidf_(a1[e] * rstd) * pf[4 + e]; }
;                     u32x4 w; w.x = cvt_pk_bf16(v0[0], v0[1]); w.y = cvt_pk_bf16(v0[2], v0[3]); w.z = cvt_pk_bf16(v1[0], v1[1]); w.w = cvt_pk_bf16(v1[2], v1[3]);
;                     *(u32x4*)(orow + bj * HALF) = w;
;                     ss += v0[0] * v0[0] + v0[1] * v0[1] + v0[2] * v0[2] + v0[3] * v0[3] + v1[0] * v1[0] + v1[1] * v1[1] + v1[2] * v1[2] + v1[3] * v1[3]; }
;                 ss += __shfl_xor(ss, 16); ss += __shfl_xor(ss, 32);
;                 if (fq == 0) atomicAdd(rowss3 + row, ss); }
	v_fmamk_f32 v215, v215, 0x3a800000, v163
	v_rsq_f32_e32 v215, v215
	v_lshlrev_b32_e32 v152, 16, v180
	v_and_b32_e32 v153, 0xffff0000, v180
	v_lshlrev_b32_e32 v155, 16, v181
	v_and_b32_e32 v159, 0xffff0000, v181
	v_lshlrev_b32_e32 v217, 16, v182
	v_and_b32_e32 v218, 0xffff0000, v182
	v_lshlrev_b32_e32 v219, 16, v183
	v_and_b32_e32 v220, 0xffff0000, v183
	v_lshlrev_b32_e32 v180, 16, v184
	v_and_b32_e32 v184, 0xffff0000, v184
	v_lshlrev_b32_e32 v181, 16, v185
	v_and_b32_e32 v185, 0xffff0000, v185
	v_lshlrev_b32_e32 v182, 16, v186
	v_and_b32_e32 v186, 0xffff0000, v186
	v_lshlrev_b32_e32 v183, 16, v187
	v_and_b32_e32 v187, 0xffff0000, v187
	v_mul_f32_e32 v60, v60, v215
	v_mul_f32_e32 v61, v61, v215
	v_mul_f32_e32 v62, v62, v215
	v_mul_f32_e32 v63, v63, v215
	v_mul_f32_e32 v56, v56, v215
	v_mul_f32_e32 v57, v57, v215
	v_mul_f32_e32 v58, v58, v215
	v_mul_f32_e32 v59, v59, v215
	v_mul_f32_e32 v60, 0xbfb8aa3b, v60
	v_mul_f32_e32 v61, 0xbfb8aa3b, v61
	v_mul_f32_e32 v62, 0xbfb8aa3b, v62
	v_mul_f32_e32 v63, 0xbfb8aa3b, v63
	v_mul_f32_e32 v56, 0xbfb8aa3b, v56
	v_mul_f32_e32 v57, 0xbfb8aa3b, v57
	v_mul_f32_e32 v58, 0xbfb8aa3b, v58
	v_mul_f32_e32 v59, 0xbfb8aa3b, v59
	v_exp_f32_e32 v60, v60
	v_exp_f32_e32 v61, v61
	v_exp_f32_e32 v62, v62
	v_exp_f32_e32 v63, v63
	v_exp_f32_e32 v56, v56
	v_exp_f32_e32 v57, v57
	v_exp_f32_e32 v58, v58
	v_exp_f32_e32 v59, v59
	v_add_f32_e32 v60, 1.0, v60
	v_add_f32_e32 v61, 1.0, v61
	v_add_f32_e32 v62, 1.0, v62
	v_add_f32_e32 v63, 1.0, v63
	v_add_f32_e32 v56, 1.0, v56
	v_add_f32_e32 v57, 1.0, v57
	v_add_f32_e32 v58, 1.0, v58
	v_add_f32_e32 v59, 1.0, v59
	v_rcp_f32_e32 v60, v60
	v_rcp_f32_e32 v61, v61
	v_rcp_f32_e32 v62, v62
	v_rcp_f32_e32 v63, v63
	v_rcp_f32_e32 v56, v56
	v_rcp_f32_e32 v57, v57
	v_rcp_f32_e32 v58, v58
	v_rcp_f32_e32 v59, v59
	v_fmac_f32_e32 v152, v60, v180
	v_fmac_f32_e32 v153, v61, v184
	v_fmac_f32_e32 v155, v62, v181
	v_fmac_f32_e32 v159, v63, v185
	v_fmac_f32_e32 v217, v56, v182
	v_fmac_f32_e32 v218, v57, v186
	v_fmac_f32_e32 v219, v58, v183
	v_fmac_f32_e32 v220, v59, v187
	v_mul_f32_e32 v63, v153, v153
	v_fmac_f32_e32 v63, v152, v152
	v_fmac_f32_e32 v63, v155, v155
	v_fmac_f32_e32 v63, v159, v159
	v_fmac_f32_e32 v63, v217, v217
	v_fmac_f32_e32 v63, v218, v218
	v_fmac_f32_e32 v63, v219, v219
	v_fmac_f32_e32 v63, v220, v220
	v_cvt_pk_bf16_f32 v180, v152, v153
	v_cvt_pk_bf16_f32 v181, v155, v159
	v_cvt_pk_bf16_f32 v182, v217, v218
	v_cvt_pk_bf16_f32 v183, v219, v220
	v_add_u32_e32 v184, 0x40000, v156
	global_store_dwordx4 v184, v[180:183], s[68:69]
	v_lshlrev_b32_e32 v152, 16, v188
	v_and_b32_e32 v153, 0xffff0000, v188
	v_lshlrev_b32_e32 v155, 16, v189
	v_and_b32_e32 v159, 0xffff0000, v189
	v_lshlrev_b32_e32 v217, 16, v190
	v_and_b32_e32 v218, 0xffff0000, v190
	v_lshlrev_b32_e32 v219, 16, v191
	v_and_b32_e32 v220, 0xffff0000, v191
	v_lshlrev_b32_e32 v188, 16, v192
	v_and_b32_e32 v192, 0xffff0000, v192
	v_lshlrev_b32_e32 v189, 16, v193
	v_and_b32_e32 v193, 0xffff0000, v193
	v_lshlrev_b32_e32 v190, 16, v194
	v_and_b32_e32 v194, 0xffff0000, v194
	v_lshlrev_b32_e32 v191, 16, v195
	v_and_b32_e32 v195, 0xffff0000, v195
	v_mul_f32_e32 v52, v52, v215
	v_mul_f32_e32 v53, v53, v215
	v_mul_f32_e32 v54, v54, v215
	v_mul_f32_e32 v55, v55, v215
	v_mul_f32_e32 v48, v48, v215
	v_mul_f32_e32 v49, v49, v215
	v_mul_f32_e32 v50, v50, v215
	v_mul_f32_e32 v51, v51, v215
	v_mul_f32_e32 v52, 0xbfb8aa3b, v52
	v_mul_f32_e32 v53, 0xbfb8aa3b, v53
	v_mul_f32_e32 v54, 0xbfb8aa3b, v54
	v_mul_f32_e32 v55, 0xbfb8aa3b, v55
	v_mul_f32_e32 v48, 0xbfb8aa3b, v48
	v_mul_f32_e32 v49, 0xbfb8aa3b, v49
	v_mul_f32_e32 v50, 0xbfb8aa3b, v50
	v_mul_f32_e32 v51, 0xbfb8aa3b, v51
	v_exp_f32_e32 v52, v52
	v_exp_f32_e32 v53, v53
	v_exp_f32_e32 v54, v54
	v_exp_f32_e32 v55, v55
	v_exp_f32_e32 v48, v48
	v_exp_f32_e32 v49, v49
	v_exp_f32_e32 v50, v50
	v_exp_f32_e32 v51, v51
	v_add_f32_e32 v52, 1.0, v52
	v_add_f32_e32 v53, 1.0, v53
	v_add_f32_e32 v54, 1.0, v54
	v_add_f32_e32 v55, 1.0, v55
	v_add_f32_e32 v48, 1.0, v48
	v_add_f32_e32 v49, 1.0, v49
	v_add_f32_e32 v50, 1.0, v50
	v_add_f32_e32 v51, 1.0, v51
	v_rcp_f32_e32 v52, v52
	v_rcp_f32_e32 v53, v53
	v_rcp_f32_e32 v54, v54
	v_rcp_f32_e32 v55, v55
	v_rcp_f32_e32 v48, v48
	v_rcp_f32_e32 v49, v49
	v_rcp_f32_e32 v50, v50
	v_rcp_f32_e32 v51, v51
	v_fmac_f32_e32 v152, v52, v188
	v_fmac_f32_e32 v153, v53, v192
	v_fmac_f32_e32 v155, v54, v189
	v_fmac_f32_e32 v159, v55, v193
	v_fmac_f32_e32 v217, v48, v190
	v_fmac_f32_e32 v218, v49, v194
	v_fmac_f32_e32 v219, v50, v191
	v_fmac_f32_e32 v220, v51, v195
	v_mul_f32_e32 v158, v153, v153
	v_fmac_f32_e32 v158, v152, v152
	v_fmac_f32_e32 v158, v155, v155
	v_fmac_f32_e32 v158, v159, v159
	v_fmac_f32_e32 v158, v217, v217
	v_fmac_f32_e32 v158, v218, v218
	v_fmac_f32_e32 v158, v219, v219
	v_fmac_f32_e32 v158, v220, v220
	v_add_f32_e32 v63, v63, v158
	s_waitcnt lgkmcnt(0)
	v_add_f32_e32 v79, v79, v78
	ds_bpermute_b32 v78, v221, v79
	ds_bpermute_b32 v62, v154, v63
	v_cvt_pk_bf16_f32 v188, v152, v153
	v_cvt_pk_bf16_f32 v189, v155, v159
	v_cvt_pk_bf16_f32 v190, v217, v218
	v_cvt_pk_bf16_f32 v191, v219, v220
	v_add_u32_e32 v192, 0x40000, v156
	global_store_dwordx4 v192, v[188:191], s[68:69] offset:256
	s_waitcnt lgkmcnt(0)
	v_add_f32_e32 v79, v79, v78
	s_mov_b64 exec, s[6:7]
	global_atomic_add_f32 v157, v79, s[12:13] offset:192
	s_mov_b64 exec, -1
	s_nop 1
	global_load_dword v215, v157, s[10:11] offset:704
	v_add_u32_e32 v158, 0x58000, v156
	global_load_dwordx4 v[180:183], v158, s[94:95]
	global_load_dwordx4 v[184:187], v158, s[76:77]
	global_load_dwordx4 v[188:191], v158, s[94:95] offset:256
	global_load_dwordx4 v[192:195], v158, s[76:77] offset:256
	s_waitcnt vmcnt(16)
; __device__ __forceinline__ void unpack8(u32x4 u, float* f) { f[0] = bflo(u.x); f[1] = bfhi(u.x); f[2] = bflo(u.y); f[3] = bfhi(u.y); f[4] = bflo(u.z); f[5] = bfhi(u.z); f[6] = bflo(u.w); f[7] = bfhi(u.w); }
; __device__ __forceinline__ float sigmoidf_(float x) { return __builtin_amdgcn_rcpf(1.f + __expf(-x)); }
; __device__ __forceinline__ unsigned cvt_pk_bf16(float lo, float hi) { unsigned r; asm volatile("v_cvt_pk_bf16_f32 %0, %1, %2" : "=v"(r) : "v"(lo), "v"(hi)); return r; }
;     __device__ __forceinline__ void operator()(const f32x4 (&acc)[2][2][4][2], const Unit& u, int wr, int wc, int fr, int fq) const {
;     ...
;             for (int m = 0; m < 4; ++m) { const int row = row0 + ai * HALF + m * 16;
;                 const float rstd = __builtin_amdgcn_rsqf(rowss2[row] * (1.f / DM) + NORM_EPS);
;                 const bf16_t* hrow = h2b + (size_t)row * DM + col0; bf16_t* orow = h3b + (size_t)row * DM + col0; const bf16_t* prow = pp + (size_t)row * DM + col0; float ss = 0.f;
; #pragma unroll
;                 for (int bj = 0; bj < 2; ++bj) { const u32x4 hw = *(const u32x4*)(hrow + bj * HALF); float hf[8]; unpack8(hw, hf);
;                     const u32x4 pw = *(const u32x4*)(prow + bj * HALF); float pf[8]; unpack8(pw, pf);
;                     const f32x4 a0 = acc[ai][bj][m][0], a1 = acc[ai][bj][m][1]; f32x4 v0, v1;
; #pragma unroll
;                     for (int e = 0; e < 4; ++e) { v0[e] = hf[e] + sigmoidf_(a0[e] * rstd) * pf[e]; v1[e] = hf[4 + e] + sigmoidf_(a1[e] * rstd) * pf[4 + e]; }
;                     u32x4 w; w.x = cvt_pk_bf16(v0[0], v0[1]); w.y = cvt_pk_bf16(v0[2], v0[3]); w.z = cvt_pk_bf16(v1[0], v1[1]); w.w = cvt_pk_bf16(v1[2], v1[3]);
;                     *(u32x4*)(orow + bj * HALF) = w;
;                     ss += v0[0] * v0[0] + v0[1] * v0[1] + v0[2] * v0[2] + v0[3] * v0[3] + v1[0] * v1[0] + v1[1] * v1[1] + v1[2] * v1[2] + v1[3] * v1[3]; }
;                 ss += __shfl_xor(ss, 16); ss += __shfl_xor(ss, 32);
;                 if (fq == 0) atomicAdd(rowss3 + row, ss); }
	v_fmamk_f32 v216, v216, 0x3a800000, v163
	v_rsq_f32_e32 v216, v216
	v_lshlrev_b32_e32 v152, 16, v196
	v_and_b32_e32 v153, 0xffff0000, v196
	v_lshlrev_b32_e32 v155, 16, v197
	v_and_b32_e32 v159, 0xffff0000, v197
	v_lshlrev_b32_e32 v217, 16, v198
	v_and_b32_e32 v218, 0xffff0000, v198
	v_lshlrev_b32_e32 v219, 16, v199
	v_and_b32_e32 v220, 0xffff0000, v199
	v_lshlrev_b32_e32 v196, 16, v200
	v_and_b32_e32 v200, 0xffff0000, v200
	v_lshlrev_b32_e32 v197, 16, v201
	v_and_b32_e32 v201, 0xffff0000, v201
	v_lshlrev_b32_e32 v198, 16, v202
	v_and_b32_e32 v202, 0xffff0000, v202
	v_lshlrev_b32_e32 v199, 16, v203
	v_and_b32_e32 v203, 0xffff0000, v203
	v_mul_f32_e32 v44, v44, v216
	v_mul_f32_e32 v45, v45, v216
	v_mul_f32_e32 v46, v46, v216
	v_mul_f32_e32 v47, v47, v216
	v_mul_f32_e32 v40, v40, v216
	v_mul_f32_e32 v41, v41, v216
	v_mul_f32_e32 v42, v42, v216
	v_mul_f32_e32 v43, v43, v216
	v_mul_f32_e32 v44, 0xbfb8aa3b, v44
	v_mul_f32_e32 v45, 0xbfb8aa3b, v45
	v_mul_f32_e32 v46, 0xbfb8aa3b, v46
	v_mul_f32_e32 v47, 0xbfb8aa3b, v47
	v_mul_f32_e32 v40, 0xbfb8aa3b, v40
	v_mul_f32_e32 v41, 0xbfb8aa3b, v41
	v_mul_f32_e32 v42, 0xbfb8aa3b, v42
	v_mul_f32_e32 v43, 0xbfb8aa3b, v43
	v_exp_f32_e32 v44, v44
	v_exp_f32_e32 v45, v45
	v_exp_f32_e32 v46, v46
	v_exp_f32_e32 v47, v47
	v_exp_f32_e32 v40, v40
	v_exp_f32_e32 v41, v41
	v_exp_f32_e32 v42, v42
	v_exp_f32_e32 v43, v43
	v_add_f32_e32 v44, 1.0, v44
	v_add_f32_e32 v45, 1.0, v45
	v_add_f32_e32 v46, 1.0, v46
	v_add_f32_e32 v47, 1.0, v47
	v_add_f32_e32 v40, 1.0, v40
	v_add_f32_e32 v41, 1.0, v41
	v_add_f32_e32 v42, 1.0, v42
	v_add_f32_e32 v43, 1.0, v43
	v_rcp_f32_e32 v44, v44
	v_rcp_f32_e32 v45, v45
	v_rcp_f32_e32 v46, v46
	v_rcp_f32_e32 v47, v47
	v_rcp_f32_e32 v40, v40
	v_rcp_f32_e32 v41, v41
	v_rcp_f32_e32 v42, v42
	v_rcp_f32_e32 v43, v43
	v_fmac_f32_e32 v152, v44, v196
	v_fmac_f32_e32 v153, v45, v200
	v_fmac_f32_e32 v155, v46, v197
	v_fmac_f32_e32 v159, v47, v201
	v_fmac_f32_e32 v217, v40, v198
	v_fmac_f32_e32 v218, v41, v202
	v_fmac_f32_e32 v219, v42, v199
	v_fmac_f32_e32 v220, v43, v203
	v_mul_f32_e32 v47, v153, v153
	v_fmac_f32_e32 v47, v152, v152
	v_fmac_f32_e32 v47, v155, v155
	v_fmac_f32_e32 v47, v159, v159
	v_fmac_f32_e32 v47, v217, v217
	v_fmac_f32_e32 v47, v218, v218
	v_fmac_f32_e32 v47, v219, v219
	v_fmac_f32_e32 v47, v220, v220
	v_cvt_pk_bf16_f32 v196, v152, v153
	v_cvt_pk_bf16_f32 v197, v155, v159
	v_cvt_pk_bf16_f32 v198, v217, v218
	v_cvt_pk_bf16_f32 v199, v219, v220
	v_add_u32_e32 v200, 0x48000, v156
	global_store_dwordx4 v200, v[196:199], s[68:69]
	v_lshlrev_b32_e32 v152, 16, v204
	v_and_b32_e32 v153, 0xffff0000, v204
	v_lshlrev_b32_e32 v155, 16, v205
	v_and_b32_e32 v159, 0xffff0000, v205
	v_lshlrev_b32_e32 v217, 16, v206
	v_and_b32_e32 v218, 0xffff0000, v206
	v_lshlrev_b32_e32 v219, 16, v207
	v_and_b32_e32 v220, 0xffff0000, v207
	v_lshlrev_b32_e32 v204, 16, v210
	v_and_b32_e32 v210, 0xffff0000, v210
	v_lshlrev_b32_e32 v205, 16, v211
	v_and_b32_e32 v211, 0xffff0000, v211
	v_lshlrev_b32_e32 v206, 16, v212
	v_and_b32_e32 v212, 0xffff0000, v212
	v_lshlrev_b32_e32 v207, 16, v213
	v_and_b32_e32 v213, 0xffff0000, v213
	v_mul_f32_e32 v36, v36, v216
	v_mul_f32_e32 v37, v37, v216
	v_mul_f32_e32 v38, v38, v216
	v_mul_f32_e32 v39, v39, v216
	v_mul_f32_e32 v32, v32, v216
	v_mul_f32_e32 v33, v33, v216
	v_mul_f32_e32 v34, v34, v216
	v_mul_f32_e32 v35, v35, v216
	v_mul_f32_e32 v36, 0xbfb8aa3b, v36
	v_mul_f32_e32 v37, 0xbfb8aa3b, v37
	v_mul_f32_e32 v38, 0xbfb8aa3b, v38
	v_mul_f32_e32 v39, 0xbfb8aa3b, v39
	v_mul_f32_e32 v32, 0xbfb8aa3b, v32
	v_mul_f32_e32 v33, 0xbfb8aa3b, v33
	v_mul_f32_e32 v34, 0xbfb8aa3b, v34
	v_mul_f32_e32 v35, 0xbfb8aa3b, v35
	v_exp_f32_e32 v36, v36
	v_exp_f32_e32 v37, v37
	v_exp_f32_e32 v38, v38
	v_exp_f32_e32 v39, v39
	v_exp_f32_e32 v32, v32
	v_exp_f32_e32 v33, v33
	v_exp_f32_e32 v34, v34
	v_exp_f32_e32 v35, v35
	v_add_f32_e32 v36, 1.0, v36
	v_add_f32_e32 v37, 1.0, v37
	v_add_f32_e32 v38, 1.0, v38
	v_add_f32_e32 v39, 1.0, v39
	v_add_f32_e32 v32, 1.0, v32
	v_add_f32_e32 v33, 1.0, v33
	v_add_f32_e32 v34, 1.0, v34
	v_add_f32_e32 v35, 1.0, v35
	v_rcp_f32_e32 v36, v36
	v_rcp_f32_e32 v37, v37
	v_rcp_f32_e32 v38, v38
	v_rcp_f32_e32 v39, v39
	v_rcp_f32_e32 v32, v32
	v_rcp_f32_e32 v33, v33
	v_rcp_f32_e32 v34, v34
	v_rcp_f32_e32 v35, v35
	v_fmac_f32_e32 v152, v36, v204
	v_fmac_f32_e32 v153, v37, v210
	v_fmac_f32_e32 v155, v38, v205
	v_fmac_f32_e32 v159, v39, v211
	v_fmac_f32_e32 v217, v32, v206
	v_fmac_f32_e32 v218, v33, v212
	v_fmac_f32_e32 v219, v34, v207
	v_fmac_f32_e32 v220, v35, v213
	v_mul_f32_e32 v158, v153, v153
	v_fmac_f32_e32 v158, v152, v152
	v_fmac_f32_e32 v158, v155, v155
	v_fmac_f32_e32 v158, v159, v159
	v_fmac_f32_e32 v158, v217, v217
	v_fmac_f32_e32 v158, v218, v218
	v_fmac_f32_e32 v158, v219, v219
	v_fmac_f32_e32 v158, v220, v220
	v_add_f32_e32 v47, v47, v158
	s_waitcnt lgkmcnt(0)
	v_add_f32_e32 v63, v63, v62
	ds_bpermute_b32 v62, v221, v63
	ds_bpermute_b32 v46, v154, v47
	v_cvt_pk_bf16_f32 v204, v152, v153
	v_cvt_pk_bf16_f32 v205, v155, v159
	v_cvt_pk_bf16_f32 v206, v217, v218
	v_cvt_pk_bf16_f32 v207, v219, v220
	v_add_u32_e32 v210, 0x48000, v156
	global_store_dwordx4 v210, v[204:207], s[68:69] offset:256
	s_waitcnt lgkmcnt(0)
	v_add_f32_e32 v63, v63, v62
	s_mov_b64 exec, s[6:7]
	global_atomic_add_f32 v157, v63, s[12:13] offset:512
	s_mov_b64 exec, -1
	s_waitcnt vmcnt(11)
; __device__ __forceinline__ void unpack8(u32x4 u, float* f) { f[0] = bflo(u.x); f[1] = bfhi(u.x); f[2] = bflo(u.y); f[3] = bfhi(u.y); f[4] = bflo(u.z); f[5] = bfhi(u.z); f[6] = bflo(u.w); f[7] = bfhi(u.w); }
; __device__ __forceinline__ float sigmoidf_(float x) { return __builtin_amdgcn_rcpf(1.f + __expf(-x)); }
; __device__ __forceinline__ unsigned cvt_pk_bf16(float lo, float hi) { unsigned r; asm volatile("v_cvt_pk_bf16_f32 %0, %1, %2" : "=v"(r) : "v"(lo), "v"(hi)); return r; }
;     __device__ __forceinline__ void operator()(const f32x4 (&acc)[2][2][4][2], const Unit& u, int wr, int wc, int fr, int fq) const {
;     ...
;             for (int m = 0; m < 4; ++m) { const int row = row0 + ai * HALF + m * 16;
;                 const float rstd = __builtin_amdgcn_rsqf(rowss2[row] * (1.f / DM) + NORM_EPS);
;                 const bf16_t* hrow = h2b + (size_t)row * DM + col0; bf16_t* orow = h3b + (size_t)row * DM + col0; const bf16_t* prow = pp + (size_t)row * DM + col0; float ss = 0.f;
; #pragma unroll
;                 for (int bj = 0; bj < 2; ++bj) { const u32x4 hw = *(const u32x4*)(hrow + bj * HALF); float hf[8]; unpack8(hw, hf);
;                     const u32x4 pw = *(const u32x4*)(prow + bj * HALF); float pf[8]; unpack8(pw, pf);
;                     const f32x4 a0 = acc[ai][bj][m][0], a1 = acc[ai][bj][m][1]; f32x4 v0, v1;
; #pragma unroll
;                     for (int e = 0; e < 4; ++e) { v0[e] = hf[e] + sigmoidf_(a0[e] * rstd) * pf[e]; v1[e] = hf[4 + e] + sigmoidf_(a1[e] * rstd) * pf[4 + e]; }
;                     u32x4 w; w.x = cvt_pk_bf16(v0[0], v0[1]); w.y = cvt_pk_bf16(v0[2], v0[3]); w.z = cvt_pk_bf16(v1[0], v1[1]); w.w = cvt_pk_bf16(v1[2], v1[3]);
;                     *(u32x4*)(orow + bj * HALF) = w;
;                     ss += v0[0] * v0[0] + v0[1] * v0[1] + v0[2] * v0[2] + v0[3] * v0[3] + v1[0] * v1[0] + v1[1] * v1[1] + v1[2] * v1[2] + v1[3] * v1[3]; }
;                 ss += __shfl_xor(ss, 16); ss += __shfl_xor(ss, 32);
;                 if (fq == 0) atomicAdd(rowss3 + row, ss); }
	v_fmamk_f32 v214, v214, 0x3a800000, v163
	v_rsq_f32_e32 v214, v214
	v_lshlrev_b32_e32 v152, 16, v164
	v_and_b32_e32 v153, 0xffff0000, v164
	v_lshlrev_b32_e32 v155, 16, v165
	v_and_b32_e32 v159, 0xffff0000, v165
	v_lshlrev_b32_e32 v217, 16, v166
	v_and_b32_e32 v218, 0xffff0000, v166
	v_lshlrev_b32_e32 v219, 16, v167
	v_and_b32_e32 v220, 0xffff0000, v167
	v_lshlrev_b32_e32 v164, 16, v168
	v_and_b32_e32 v168, 0xffff0000, v168
	v_lshlrev_b32_e32 v165, 16, v169
	v_and_b32_e32 v169, 0xffff0000, v169
	v_lshlrev_b32_e32 v166, 16, v170
	v_and_b32_e32 v170, 0xffff0000, v170
	v_lshlrev_b32_e32 v167, 16, v171
	v_and_b32_e32 v171, 0xffff0000, v171
	v_mul_f32_e32 v28, v28, v214
	v_mul_f32_e32 v29, v29, v214
	v_mul_f32_e32 v30, v30, v214
	v_mul_f32_e32 v31, v31, v214
	v_mul_f32_e32 v24, v24, v214
	v_mul_f32_e32 v25, v25, v214
	v_mul_f32_e32 v26, v26, v214
	v_mul_f32_e32 v27, v27, v214
	v_mul_f32_e32 v28, 0xbfb8aa3b, v28
	v_mul_f32_e32 v29, 0xbfb8aa3b, v29
	v_mul_f32_e32 v30, 0xbfb8aa3b, v30
	v_mul_f32_e32 v31, 0xbfb8aa3b, v31
	v_mul_f32_e32 v24, 0xbfb8aa3b, v24
	v_mul_f32_e32 v25, 0xbfb8aa3b, v25
	v_mul_f32_e32 v26, 0xbfb8aa3b, v26
	v_mul_f32_e32 v27, 0xbfb8aa3b, v27
	v_exp_f32_e32 v28, v28
	v_exp_f32_e32 v29, v29
	v_exp_f32_e32 v30, v30
	v_exp_f32_e32 v31, v31
	v_exp_f32_e32 v24, v24
	v_exp_f32_e32 v25, v25
	v_exp_f32_e32 v26, v26
	v_exp_f32_e32 v27, v27
	v_add_f32_e32 v28, 1.0, v28
	v_add_f32_e32 v29, 1.0, v29
	v_add_f32_e32 v30, 1.0, v30
	v_add_f32_e32 v31, 1.0, v31
	v_add_f32_e32 v24, 1.0, v24
	v_add_f32_e32 v25, 1.0, v25
	v_add_f32_e32 v26, 1.0, v26
	v_add_f32_e32 v27, 1.0, v27
	v_rcp_f32_e32 v28, v28
	v_rcp_f32_e32 v29, v29
	v_rcp_f32_e32 v30, v30
	v_rcp_f32_e32 v31, v31
	v_rcp_f32_e32 v24, v24
	v_rcp_f32_e32 v25, v25
	v_rcp_f32_e32 v26, v26
	v_rcp_f32_e32 v27, v27
	v_fmac_f32_e32 v152, v28, v164
	v_fmac_f32_e32 v153, v29, v168
	v_fmac_f32_e32 v155, v30, v165
	v_fmac_f32_e32 v159, v31, v169
	v_fmac_f32_e32 v217, v24, v166
	v_fmac_f32_e32 v218, v25, v170
	v_fmac_f32_e32 v219, v26, v167
	v_fmac_f32_e32 v220, v27, v171
	v_mul_f32_e32 v31, v153, v153
	v_fmac_f32_e32 v31, v152, v152
	v_fmac_f32_e32 v31, v155, v155
	v_fmac_f32_e32 v31, v159, v159
	v_fmac_f32_e32 v31, v217, v217
	v_fmac_f32_e32 v31, v218, v218
	v_fmac_f32_e32 v31, v219, v219
	v_fmac_f32_e32 v31, v220, v220
	v_cvt_pk_bf16_f32 v164, v152, v153
	v_cvt_pk_bf16_f32 v165, v155, v159
	v_cvt_pk_bf16_f32 v166, v217, v218
	v_cvt_pk_bf16_f32 v167, v219, v220
	v_add_u32_e32 v168, 0x50000, v156
	global_store_dwordx4 v168, v[164:167], s[68:69]
	v_lshlrev_b32_e32 v152, 16, v172
	v_and_b32_e32 v153, 0xffff0000, v172
	v_lshlrev_b32_e32 v155, 16, v173
	v_and_b32_e32 v159, 0xffff0000, v173
	v_lshlrev_b32_e32 v217, 16, v174
	v_and_b32_e32 v218, 0xffff0000, v174
	v_lshlrev_b32_e32 v219, 16, v175
	v_and_b32_e32 v220, 0xffff0000, v175
	v_lshlrev_b32_e32 v172, 16, v176
	v_and_b32_e32 v176, 0xffff0000, v176
	v_lshlrev_b32_e32 v173, 16, v177
	v_and_b32_e32 v177, 0xffff0000, v177
	v_lshlrev_b32_e32 v174, 16, v178
	v_and_b32_e32 v178, 0xffff0000, v178
	v_lshlrev_b32_e32 v175, 16, v179
	v_and_b32_e32 v179, 0xffff0000, v179
	v_mul_f32_e32 v20, v20, v214
	v_mul_f32_e32 v21, v21, v214
	v_mul_f32_e32 v22, v22, v214
	v_mul_f32_e32 v23, v23, v214
	v_mul_f32_e32 v16, v16, v214
	v_mul_f32_e32 v17, v17, v214
	v_mul_f32_e32 v18, v18, v214
	v_mul_f32_e32 v19, v19, v214
	v_mul_f32_e32 v20, 0xbfb8aa3b, v20
	v_mul_f32_e32 v21, 0xbfb8aa3b, v21
	v_mul_f32_e32 v22, 0xbfb8aa3b, v22
	v_mul_f32_e32 v23, 0xbfb8aa3b, v23
	v_mul_f32_e32 v16, 0xbfb8aa3b, v16
	v_mul_f32_e32 v17, 0xbfb8aa3b, v17
	v_mul_f32_e32 v18, 0xbfb8aa3b, v18
	v_mul_f32_e32 v19, 0xbfb8aa3b, v19
	v_exp_f32_e32 v20, v20
	v_exp_f32_e32 v21, v21
	v_exp_f32_e32 v22, v22
	v_exp_f32_e32 v23, v23
	v_exp_f32_e32 v16, v16
	v_exp_f32_e32 v17, v17
	v_exp_f32_e32 v18, v18
	v_exp_f32_e32 v19, v19
	v_add_f32_e32 v20, 1.0, v20
	v_add_f32_e32 v21, 1.0, v21
	v_add_f32_e32 v22, 1.0, v22
	v_add_f32_e32 v23, 1.0, v23
	v_add_f32_e32 v16, 1.0, v16
	v_add_f32_e32 v17, 1.0, v17
	v_add_f32_e32 v18, 1.0, v18
	v_add_f32_e32 v19, 1.0, v19
	v_rcp_f32_e32 v20, v20
	v_rcp_f32_e32 v21, v21
	v_rcp_f32_e32 v22, v22
	v_rcp_f32_e32 v23, v23
	v_rcp_f32_e32 v16, v16
	v_rcp_f32_e32 v17, v17
	v_rcp_f32_e32 v18, v18
	v_rcp_f32_e32 v19, v19
	v_fmac_f32_e32 v152, v20, v172
	v_fmac_f32_e32 v153, v21, v176
	v_fmac_f32_e32 v155, v22, v173
	v_fmac_f32_e32 v159, v23, v177
	v_fmac_f32_e32 v217, v16, v174
	v_fmac_f32_e32 v218, v17, v178
	v_fmac_f32_e32 v219, v18, v175
	v_fmac_f32_e32 v220, v19, v179
	v_mul_f32_e32 v158, v153, v153
	v_fmac_f32_e32 v158, v152, v152
	v_fmac_f32_e32 v158, v155, v155
	v_fmac_f32_e32 v158, v159, v159
	v_fmac_f32_e32 v158, v217, v217
	v_fmac_f32_e32 v158, v218, v218
	v_fmac_f32_e32 v158, v219, v219
	v_fmac_f32_e32 v158, v220, v220
	v_add_f32_e32 v31, v31, v158
	s_waitcnt lgkmcnt(0)
	v_add_f32_e32 v47, v47, v46
	ds_bpermute_b32 v46, v221, v47
	ds_bpermute_b32 v30, v154, v31
	v_cvt_pk_bf16_f32 v172, v152, v153
	v_cvt_pk_bf16_f32 v173, v155, v159
	v_cvt_pk_bf16_f32 v174, v217, v218
	v_cvt_pk_bf16_f32 v175, v219, v220
	v_add_u32_e32 v176, 0x50000, v156
	global_store_dwordx4 v176, v[172:175], s[68:69] offset:256
	s_waitcnt lgkmcnt(0)
	v_add_f32_e32 v47, v47, v46
	s_mov_b64 exec, s[6:7]
	global_atomic_add_f32 v157, v47, s[12:13] offset:576
	s_mov_b64 exec, -1
	s_waitcnt vmcnt(6)
; __device__ __forceinline__ void unpack8(u32x4 u, float* f) { f[0] = bflo(u.x); f[1] = bfhi(u.x); f[2] = bflo(u.y); f[3] = bfhi(u.y); f[4] = bflo(u.z); f[5] = bfhi(u.z); f[6] = bflo(u.w); f[7] = bfhi(u.w); }
; __device__ __forceinline__ float sigmoidf_(float x) { return __builtin_amdgcn_rcpf(1.f + __expf(-x)); }
; __device__ __forceinline__ unsigned cvt_pk_bf16(float lo, float hi) { unsigned r; asm volatile("v_cvt_pk_bf16_f32 %0, %1, %2" : "=v"(r) : "v"(lo), "v"(hi)); return r; }
;     __device__ __forceinline__ void operator()(const f32x4 (&acc)[2][2][4][2], const Unit& u, int wr, int wc, int fr, int fq) const {
;     ...
;             for (int m = 0; m < 4; ++m) { const int row = row0 + ai * HALF + m * 16;
;                 const float rstd = __builtin_amdgcn_rsqf(rowss2[row] * (1.f / DM) + NORM_EPS);
;                 const bf16_t* hrow = h2b + (size_t)row * DM + col0; bf16_t* orow = h3b + (size_t)row * DM + col0; const bf16_t* prow = pp + (size_t)row * DM + col0; float ss = 0.f;
; #pragma unroll
;                 for (int bj = 0; bj < 2; ++bj) { const u32x4 hw = *(const u32x4*)(hrow + bj * HALF); float hf[8]; unpack8(hw, hf);
;                     const u32x4 pw = *(const u32x4*)(prow + bj * HALF); float pf[8]; unpack8(pw, pf);
;                     const f32x4 a0 = acc[ai][bj][m][0], a1 = acc[ai][bj][m][1]; f32x4 v0, v1;
; #pragma unroll
;                     for (int e = 0; e < 4; ++e) { v0[e] = hf[e] + sigmoidf_(a0[e] * rstd) * pf[e]; v1[e] = hf[4 + e] + sigmoidf_(a1[e] * rstd) * pf[4 + e]; }
;                     u32x4 w; w.x = cvt_pk_bf16(v0[0], v0[1]); w.y = cvt_pk_bf16(v0[2], v0[3]); w.z = cvt_pk_bf16(v1[0], v1[1]); w.w = cvt_pk_bf16(v1[2], v1[3]);
;                     *(u32x4*)(orow + bj * HALF) = w;
;                     ss += v0[0] * v0[0] + v0[1] * v0[1] + v0[2] * v0[2] + v0[3] * v0[3] + v1[0] * v1[0] + v1[1] * v1[1] + v1[2] * v1[2] + v1[3] * v1[3]; }
;                 ss += __shfl_xor(ss, 16); ss += __shfl_xor(ss, 32);
;                 if (fq == 0) atomicAdd(rowss3 + row, ss); }
;     }
	v_fmamk_f32 v215, v215, 0x3a800000, v163
	v_rsq_f32_e32 v215, v215
	v_lshlrev_b32_e32 v152, 16, v180
	v_and_b32_e32 v153, 0xffff0000, v180
	v_lshlrev_b32_e32 v155, 16, v181
	v_and_b32_e32 v159, 0xffff0000, v181
	v_lshlrev_b32_e32 v217, 16, v182
	v_and_b32_e32 v218, 0xffff0000, v182
	v_lshlrev_b32_e32 v219, 16, v183
	v_and_b32_e32 v220, 0xffff0000, v183
	v_lshlrev_b32_e32 v180, 16, v184
	v_and_b32_e32 v184, 0xffff0000, v184
	v_lshlrev_b32_e32 v181, 16, v185
	v_and_b32_e32 v185, 0xffff0000, v185
	v_lshlrev_b32_e32 v182, 16, v186
	v_and_b32_e32 v186, 0xffff0000, v186
	v_lshlrev_b32_e32 v183, 16, v187
	v_and_b32_e32 v187, 0xffff0000, v187
	v_mul_f32_e32 v12, v12, v215
	v_mul_f32_e32 v13, v13, v215
	v_mul_f32_e32 v14, v14, v215
	v_mul_f32_e32 v15, v15, v215
	v_mul_f32_e32 v8, v8, v215
	v_mul_f32_e32 v9, v9, v215
	v_mul_f32_e32 v10, v10, v215
	v_mul_f32_e32 v11, v11, v215
	v_mul_f32_e32 v12, 0xbfb8aa3b, v12
	v_mul_f32_e32 v13, 0xbfb8aa3b, v13
	v_mul_f32_e32 v14, 0xbfb8aa3b, v14
	v_mul_f32_e32 v15, 0xbfb8aa3b, v15
	v_mul_f32_e32 v8, 0xbfb8aa3b, v8
	v_mul_f32_e32 v9, 0xbfb8aa3b, v9
	v_mul_f32_e32 v10, 0xbfb8aa3b, v10
	v_mul_f32_e32 v11, 0xbfb8aa3b, v11
	v_exp_f32_e32 v12, v12
	v_exp_f32_e32 v13, v13
	v_exp_f32_e32 v14, v14
	v_exp_f32_e32 v15, v15
	v_exp_f32_e32 v8, v8
	v_exp_f32_e32 v9, v9
	v_exp_f32_e32 v10, v10
	v_exp_f32_e32 v11, v11
	v_add_f32_e32 v12, 1.0, v12
	v_add_f32_e32 v13, 1.0, v13
	v_add_f32_e32 v14, 1.0, v14
	v_add_f32_e32 v15, 1.0, v15
	v_add_f32_e32 v8, 1.0, v8
	v_add_f32_e32 v9, 1.0, v9
	v_add_f32_e32 v10, 1.0, v10
	v_add_f32_e32 v11, 1.0, v11
	v_rcp_f32_e32 v12, v12
	v_rcp_f32_e32 v13, v13
	v_rcp_f32_e32 v14, v14
	v_rcp_f32_e32 v15, v15
	v_rcp_f32_e32 v8, v8
	v_rcp_f32_e32 v9, v9
	v_rcp_f32_e32 v10, v10
	v_rcp_f32_e32 v11, v11
	v_fmac_f32_e32 v152, v12, v180
	v_fmac_f32_e32 v153, v13, v184
	v_fmac_f32_e32 v155, v14, v181
	v_fmac_f32_e32 v159, v15, v185
	v_fmac_f32_e32 v217, v8, v182
	v_fmac_f32_e32 v218, v9, v186
	v_fmac_f32_e32 v219, v10, v183
	v_fmac_f32_e32 v220, v11, v187
	v_mul_f32_e32 v15, v153, v153
	v_fmac_f32_e32 v15, v152, v152
	v_fmac_f32_e32 v15, v155, v155
	v_fmac_f32_e32 v15, v159, v159
	v_fmac_f32_e32 v15, v217, v217
	v_fmac_f32_e32 v15, v218, v218
	v_fmac_f32_e32 v15, v219, v219
	v_fmac_f32_e32 v15, v220, v220
	v_cvt_pk_bf16_f32 v180, v152, v153
	v_cvt_pk_bf16_f32 v181, v155, v159
	v_cvt_pk_bf16_f32 v182, v217, v218
	v_cvt_pk_bf16_f32 v183, v219, v220
	v_add_u32_e32 v184, 0x58000, v156
	global_store_dwordx4 v184, v[180:183], s[68:69]
	v_lshlrev_b32_e32 v152, 16, v188
	v_and_b32_e32 v153, 0xffff0000, v188
	v_lshlrev_b32_e32 v155, 16, v189
	v_and_b32_e32 v159, 0xffff0000, v189
	v_lshlrev_b32_e32 v217, 16, v190
	v_and_b32_e32 v218, 0xffff0000, v190
	v_lshlrev_b32_e32 v219, 16, v191
	v_and_b32_e32 v220, 0xffff0000, v191
	v_lshlrev_b32_e32 v188, 16, v192
	v_and_b32_e32 v192, 0xffff0000, v192
	v_lshlrev_b32_e32 v189, 16, v193
	v_and_b32_e32 v193, 0xffff0000, v193
	v_lshlrev_b32_e32 v190, 16, v194
	v_and_b32_e32 v194, 0xffff0000, v194
	v_lshlrev_b32_e32 v191, 16, v195
	v_and_b32_e32 v195, 0xffff0000, v195
	v_mul_f32_e32 v4, v4, v215
	v_mul_f32_e32 v5, v5, v215
	v_mul_f32_e32 v6, v6, v215
	v_mul_f32_e32 v7, v7, v215
	v_mul_f32_e32 v0, v0, v215
	v_mul_f32_e32 v1, v1, v215
	v_mul_f32_e32 v2, v2, v215
	v_mul_f32_e32 v3, v3, v215
	v_mul_f32_e32 v4, 0xbfb8aa3b, v4
	v_mul_f32_e32 v5, 0xbfb8aa3b, v5
	v_mul_f32_e32 v6, 0xbfb8aa3b, v6
	v_mul_f32_e32 v7, 0xbfb8aa3b, v7
	v_mul_f32_e32 v0, 0xbfb8aa3b, v0
	v_mul_f32_e32 v1, 0xbfb8aa3b, v1
	v_mul_f32_e32 v2, 0xbfb8aa3b, v2
	v_mul_f32_e32 v3, 0xbfb8aa3b, v3
	v_exp_f32_e32 v4, v4
	v_exp_f32_e32 v5, v5
	v_exp_f32_e32 v6, v6
	v_exp_f32_e32 v7, v7
	v_exp_f32_e32 v0, v0
	v_exp_f32_e32 v1, v1
	v_exp_f32_e32 v2, v2
	v_exp_f32_e32 v3, v3
	v_add_f32_e32 v4, 1.0, v4
	v_add_f32_e32 v5, 1.0, v5
	v_add_f32_e32 v6, 1.0, v6
	v_add_f32_e32 v7, 1.0, v7
	v_add_f32_e32 v0, 1.0, v0
	v_add_f32_e32 v1, 1.0, v1
	v_add_f32_e32 v2, 1.0, v2
	v_add_f32_e32 v3, 1.0, v3
	v_rcp_f32_e32 v4, v4
	v_rcp_f32_e32 v5, v5
	v_rcp_f32_e32 v6, v6
	v_rcp_f32_e32 v7, v7
	v_rcp_f32_e32 v0, v0
	v_rcp_f32_e32 v1, v1
	v_rcp_f32_e32 v2, v2
	v_rcp_f32_e32 v3, v3
	v_fmac_f32_e32 v152, v4, v188
	v_fmac_f32_e32 v153, v5, v192
	v_fmac_f32_e32 v155, v6, v189
	v_fmac_f32_e32 v159, v7, v193
	v_fmac_f32_e32 v217, v0, v190
	v_fmac_f32_e32 v218, v1, v194
	v_fmac_f32_e32 v219, v2, v191
	v_fmac_f32_e32 v220, v3, v195
	v_mul_f32_e32 v158, v153, v153
	v_fmac_f32_e32 v158, v152, v152
	v_fmac_f32_e32 v158, v155, v155
	v_fmac_f32_e32 v158, v159, v159
	v_fmac_f32_e32 v158, v217, v217
	v_fmac_f32_e32 v158, v218, v218
	v_fmac_f32_e32 v158, v219, v219
	v_fmac_f32_e32 v158, v220, v220
	v_add_f32_e32 v15, v15, v158
	s_waitcnt lgkmcnt(0)
	v_add_f32_e32 v31, v31, v30
	ds_bpermute_b32 v30, v221, v31
	ds_bpermute_b32 v14, v154, v15
	v_cvt_pk_bf16_f32 v188, v152, v153
	v_cvt_pk_bf16_f32 v189, v155, v159
	v_cvt_pk_bf16_f32 v190, v217, v218
	v_cvt_pk_bf16_f32 v191, v219, v220
	v_add_u32_e32 v192, 0x58000, v156
	global_store_dwordx4 v192, v[188:191], s[68:69] offset:256
	s_waitcnt lgkmcnt(0)
	v_add_f32_e32 v31, v31, v30
	s_mov_b64 exec, s[6:7]
	global_atomic_add_f32 v157, v31, s[12:13] offset:640
	s_mov_b64 exec, -1
	s_waitcnt lgkmcnt(0)
	v_add_f32_e32 v15, v15, v14
	ds_bpermute_b32 v14, v221, v15
	s_waitcnt lgkmcnt(0)
	v_add_f32_e32 v15, v15, v14
	s_mov_b64 exec, s[6:7]
	global_atomic_add_f32 v157, v15, s[12:13] offset:704
	s_mov_b64 exec, -1
